# int8 GEMM epilogues read row/column scales from per-wave LDS slots staged by LDS-DMA at unit start (no vmcnt(0) behind next-unit staging loads); GEMM K loops: first iteration peeled with SrcC=0, accum
# speedup vs baseline: 1.0048x; 1.0048x over previous
.LBB0_758:
	s_ashr_i32 s37, s36, 31
	s_lshl_b64 s[34:35], s[36:37], 21
	s_add_u32 s64, s48, s34
	s_addc_u32 s65, s49, s35
	s_and_b64 s[34:35], s[4:5], exec
	s_cselect_b32 s15, s65, s7
	s_cselect_b32 s33, s64, s6
	s_ashr_i32 s31, s30, 31
	s_lshl_b64 s[34:35], s[30:31], 21
	s_add_u32 s34, s52, s34
	s_addc_u32 s35, s53, s35
	s_and_b64 s[42:43], s[4:5], exec
	s_cselect_b32 s31, s35, s9
	s_cselect_b32 s37, s34, s8
	s_add_u32 s6, s6, 0x100080
	s_addc_u32 s7, s7, 0
	s_add_u32 s40, s8, 0x100
	s_waitcnt lgkmcnt(0)
	s_addc_u32 s44, s9, 0
	s_mov_b32 s45, -2
	s_add_u32 s8, s6, 0xfff00080
	s_addc_u32 s9, s7, -1
	s_add_i32 s46, 0, 0x10000
	s_cmp_eq_u32 s45, 60
	s_cselect_b32 s43, s15, s9
	s_cselect_b32 s42, s33, s8
	v_add_u32_e32 v2, s46, v154
	s_cselect_b32 s9, s31, s44
	s_cselect_b32 s8, s37, s40
	s_add_i32 s51, 0, 0x14000
	ds_read_b128 v[144:147], v2
	ds_read_b128 v[148:151], v2 offset:1024
	ds_read_b128 v[156:159], v2 offset:2048
	ds_read_b128 v[160:163], v2 offset:3072
	v_add_u32_e32 v2, s51, v154
	ds_read_b128 v[164:167], v2
	ds_read_b128 v[168:171], v2 offset:1024
	ds_read_b128 v[172:175], v2 offset:2048
	ds_read_b128 v[176:179], v2 offset:3072
	v_lshl_add_u64 v[196:197], s[6:7], 0, v[140:141]
	s_add_i32 m0, s55, 0xc000
	ds_read_b128 v[180:183], v155
	ds_read_b128 v[184:187], v155 offset:1024
	ds_read_b128 v[188:191], v155 offset:2048
	ds_read_b128 v[192:195], v155 offset:3072
	ds_read_b128 v[204:207], v155 offset:4096
	ds_read_b128 v[208:211], v155 offset:5120
	ds_read_b128 v[230:233], v155 offset:6144
	ds_read_b128 v[234:237], v155 offset:7168
	global_load_lds_dwordx4 v[196:197], off
	v_lshl_add_u64 v[196:197], s[6:7], 0, v[142:143]
	s_add_i32 m0, s55, 0xe000
	s_nop 0
	global_load_lds_dwordx4 v[196:197], off
	s_waitcnt vmcnt(8)
	s_waitcnt lgkmcnt(0)
	s_barrier
	v_mfma_f32_16x16x32_bf16 v[64:67], v[144:147], v[180:183], 0
	v_mfma_f32_16x16x32_bf16 v[60:63], v[156:159], v[180:183], 0
	v_mfma_f32_16x16x32_bf16 v[56:59], v[144:147], v[188:191], 0
	v_mfma_f32_16x16x32_bf16 v[52:55], v[156:159], v[188:191], 0
	v_mfma_f32_16x16x32_bf16 v[48:51], v[144:147], v[204:207], 0
	v_mfma_f32_16x16x32_bf16 v[44:47], v[156:159], v[204:207], 0
	v_mfma_f32_16x16x32_bf16 v[40:43], v[144:147], v[230:233], 0
	v_mfma_f32_16x16x32_bf16 v[36:39], v[156:159], v[230:233], 0
	v_mfma_f32_16x16x32_bf16 v[64:67], v[148:151], v[184:187], v[64:67]
	v_mfma_f32_16x16x32_bf16 v[60:63], v[160:163], v[184:187], v[60:63]
	v_mfma_f32_16x16x32_bf16 v[56:59], v[148:151], v[192:195], v[56:59]
	v_mfma_f32_16x16x32_bf16 v[52:55], v[160:163], v[192:195], v[52:55]
	v_mfma_f32_16x16x32_bf16 v[48:51], v[148:151], v[208:211], v[48:51]
	v_mfma_f32_16x16x32_bf16 v[44:47], v[160:163], v[208:211], v[44:47]
	v_mfma_f32_16x16x32_bf16 v[40:43], v[148:151], v[234:237], v[40:43]
	v_mfma_f32_16x16x32_bf16 v[36:39], v[160:163], v[234:237], v[36:39]
	v_mfma_f32_16x16x32_bf16 v[128:131], v[164:167], v[180:183], 0
	v_mfma_f32_16x16x32_bf16 v[124:127], v[172:175], v[180:183], 0
	v_mfma_f32_16x16x32_bf16 v[120:123], v[164:167], v[188:191], 0
	v_mfma_f32_16x16x32_bf16 v[116:119], v[172:175], v[188:191], 0
	v_mfma_f32_16x16x32_bf16 v[112:115], v[164:167], v[204:207], 0
	v_mfma_f32_16x16x32_bf16 v[108:111], v[172:175], v[204:207], 0
	v_mfma_f32_16x16x32_bf16 v[104:107], v[164:167], v[230:233], 0
	v_mfma_f32_16x16x32_bf16 v[100:103], v[172:175], v[230:233], 0
	v_mfma_f32_16x16x32_bf16 v[128:131], v[168:171], v[184:187], v[128:131]
	v_mfma_f32_16x16x32_bf16 v[124:127], v[176:179], v[184:187], v[124:127]
	v_mfma_f32_16x16x32_bf16 v[120:123], v[168:171], v[192:195], v[120:123]
	v_mfma_f32_16x16x32_bf16 v[116:119], v[176:179], v[192:195], v[116:119]
	v_mfma_f32_16x16x32_bf16 v[112:115], v[168:171], v[208:211], v[112:115]
	v_mfma_f32_16x16x32_bf16 v[108:111], v[176:179], v[208:211], v[108:111]
	v_mfma_f32_16x16x32_bf16 v[104:107], v[168:171], v[234:237], v[104:107]
	v_mfma_f32_16x16x32_bf16 v[100:103], v[176:179], v[234:237], v[100:103]
	s_barrier
	s_add_i32 s46, s46, s54
	v_lshl_add_u64 v[196:197], s[8:9], 0, v[136:137]
	s_mov_b32 m0, s46
	ds_read_b128 v[180:183], v155 offset:16384
	ds_read_b128 v[184:187], v155 offset:17408
	ds_read_b128 v[188:191], v155 offset:18432
	ds_read_b128 v[192:195], v155 offset:19456
	ds_read_b128 v[204:207], v155 offset:20480
	ds_read_b128 v[208:211], v155 offset:21504
	ds_read_b128 v[230:233], v155 offset:22528
	ds_read_b128 v[234:237], v155 offset:23552
	global_load_lds_dwordx4 v[196:197], off
	s_add_i32 m0, s46, 0x2000
	s_add_u32 s46, s8, 0x100000
	v_lshl_add_u64 v[198:199], s[8:9], 0, v[132:133]
	s_addc_u32 s47, s9, 0
	s_add_i32 s51, s51, s54
	global_load_lds_dwordx4 v[198:199], off
	v_lshl_add_u64 v[212:213], s[46:47], 0, v[136:137]
	s_mov_b32 m0, s51
	v_lshl_add_u64 v[214:215], s[42:43], 0, v[134:135]
	global_load_lds_dwordx4 v[212:213], off
	v_lshl_add_u64 v[212:213], s[46:47], 0, v[132:133]
	s_add_i32 m0, s51, 0x2000
	s_nop 0
	global_load_lds_dwordx4 v[212:213], off
	v_lshl_add_u64 v[212:213], s[42:43], 0, v[138:139]
	s_mov_b32 m0, s55
	s_nop 0
	global_load_lds_dwordx4 v[212:213], off
	s_mov_b32 m0, s56
	s_nop 0
	global_load_lds_dwordx4 v[214:215], off
	s_waitcnt vmcnt(8)
	s_waitcnt lgkmcnt(0)
	s_barrier
	v_mfma_f32_16x16x32_bf16 v[32:35], v[144:147], v[180:183], 0
	v_mfma_f32_16x16x32_bf16 v[28:31], v[156:159], v[180:183], 0
	v_mfma_f32_16x16x32_bf16 v[24:27], v[144:147], v[188:191], 0
	v_mfma_f32_16x16x32_bf16 v[20:23], v[156:159], v[188:191], 0
	v_mfma_f32_16x16x32_bf16 v[16:19], v[144:147], v[204:207], 0
	v_mfma_f32_16x16x32_bf16 v[12:15], v[156:159], v[204:207], 0
	v_mfma_f32_16x16x32_bf16 v[8:11], v[144:147], v[230:233], 0
	v_mfma_f32_16x16x32_bf16 v[4:7], v[156:159], v[230:233], 0
	v_mfma_f32_16x16x32_bf16 v[32:35], v[148:151], v[184:187], v[32:35]
	v_mfma_f32_16x16x32_bf16 v[28:31], v[160:163], v[184:187], v[28:31]
	v_mfma_f32_16x16x32_bf16 v[24:27], v[148:151], v[192:195], v[24:27]
	v_mfma_f32_16x16x32_bf16 v[20:23], v[160:163], v[192:195], v[20:23]
	v_mfma_f32_16x16x32_bf16 v[16:19], v[148:151], v[208:211], v[16:19]
	v_mfma_f32_16x16x32_bf16 v[12:15], v[160:163], v[208:211], v[12:15]
	v_mfma_f32_16x16x32_bf16 v[8:11], v[148:151], v[234:237], v[8:11]
	v_mfma_f32_16x16x32_bf16 v[4:7], v[160:163], v[234:237], v[4:7]
	v_mfma_f32_16x16x32_bf16 v[96:99], v[164:167], v[180:183], 0
	v_mfma_f32_16x16x32_bf16 v[92:95], v[172:175], v[180:183], 0
	v_mfma_f32_16x16x32_bf16 v[88:91], v[164:167], v[188:191], 0
	v_mfma_f32_16x16x32_bf16 v[84:87], v[172:175], v[188:191], 0
	v_mfma_f32_16x16x32_bf16 v[80:83], v[164:167], v[204:207], 0
	v_mfma_f32_16x16x32_bf16 v[76:79], v[172:175], v[204:207], 0
	v_mfma_f32_16x16x32_bf16 v[72:75], v[164:167], v[230:233], 0
	v_mfma_f32_16x16x32_bf16 v[68:71], v[172:175], v[230:233], 0
	v_mfma_f32_16x16x32_bf16 v[96:99], v[168:171], v[184:187], v[96:99]
	v_mfma_f32_16x16x32_bf16 v[92:95], v[176:179], v[184:187], v[92:95]
	v_mfma_f32_16x16x32_bf16 v[88:91], v[168:171], v[192:195], v[88:91]
	v_mfma_f32_16x16x32_bf16 v[84:87], v[176:179], v[192:195], v[84:87]
	v_mfma_f32_16x16x32_bf16 v[80:83], v[168:171], v[208:211], v[80:83]
	v_mfma_f32_16x16x32_bf16 v[76:79], v[176:179], v[208:211], v[76:79]
	v_mfma_f32_16x16x32_bf16 v[72:75], v[168:171], v[234:237], v[72:75]
	v_mfma_f32_16x16x32_bf16 v[68:71], v[176:179], v[234:237], v[68:71]
	s_barrier
	s_add_i32 s46, 0, 0x18000
	v_add_u32_e32 v2, s46, v154
	s_add_i32 s47, 0, 0x1c000
	ds_read_b128 v[144:147], v2
	ds_read_b128 v[148:151], v2 offset:1024
	ds_read_b128 v[156:159], v2 offset:2048
	ds_read_b128 v[160:163], v2 offset:3072
	v_add_u32_e32 v2, s47, v154
	ds_read_b128 v[164:167], v2
	ds_read_b128 v[168:171], v2 offset:1024
	ds_read_b128 v[172:175], v2 offset:2048
	ds_read_b128 v[176:179], v2 offset:3072
	s_add_u32 s42, s42, 0x100000
	s_addc_u32 s43, s43, 0
	s_mov_b32 m0, s57
	v_lshl_add_u64 v[226:227], s[42:43], 0, v[138:139]
	ds_read_b128 v[180:183], v155 offset:32768
	ds_read_b128 v[184:187], v155 offset:33792
	ds_read_b128 v[188:191], v155 offset:34816
	ds_read_b128 v[192:195], v155 offset:35840
	ds_read_b128 v[204:207], v155 offset:36864
	ds_read_b128 v[208:211], v155 offset:37888
	ds_read_b128 v[230:233], v155 offset:38912
	ds_read_b128 v[234:237], v155 offset:39936
	global_load_lds_dwordx4 v[226:227], off
	v_lshl_add_u64 v[226:227], s[42:43], 0, v[134:135]
	s_mov_b32 m0, s87
	s_nop 0
	global_load_lds_dwordx4 v[226:227], off
	s_waitcnt vmcnt(8)
	s_waitcnt lgkmcnt(0)
	s_barrier
	v_mfma_f32_16x16x32_bf16 v[64:67], v[144:147], v[180:183], v[64:67]
	v_mfma_f32_16x16x32_bf16 v[60:63], v[156:159], v[180:183], v[60:63]
	v_mfma_f32_16x16x32_bf16 v[56:59], v[144:147], v[188:191], v[56:59]
	v_mfma_f32_16x16x32_bf16 v[52:55], v[156:159], v[188:191], v[52:55]
	v_mfma_f32_16x16x32_bf16 v[48:51], v[144:147], v[204:207], v[48:51]
	v_mfma_f32_16x16x32_bf16 v[44:47], v[156:159], v[204:207], v[44:47]
	v_mfma_f32_16x16x32_bf16 v[40:43], v[144:147], v[230:233], v[40:43]
	v_mfma_f32_16x16x32_bf16 v[36:39], v[156:159], v[230:233], v[36:39]
	v_mfma_f32_16x16x32_bf16 v[64:67], v[148:151], v[184:187], v[64:67]
	v_mfma_f32_16x16x32_bf16 v[60:63], v[160:163], v[184:187], v[60:63]
	v_mfma_f32_16x16x32_bf16 v[56:59], v[148:151], v[192:195], v[56:59]
	v_mfma_f32_16x16x32_bf16 v[52:55], v[160:163], v[192:195], v[52:55]
	v_mfma_f32_16x16x32_bf16 v[48:51], v[148:151], v[208:211], v[48:51]
	v_mfma_f32_16x16x32_bf16 v[44:47], v[160:163], v[208:211], v[44:47]
	v_mfma_f32_16x16x32_bf16 v[40:43], v[148:151], v[234:237], v[40:43]
	v_mfma_f32_16x16x32_bf16 v[36:39], v[160:163], v[234:237], v[36:39]
	v_mfma_f32_16x16x32_bf16 v[128:131], v[164:167], v[180:183], v[128:131]
	v_mfma_f32_16x16x32_bf16 v[124:127], v[172:175], v[180:183], v[124:127]
	v_mfma_f32_16x16x32_bf16 v[120:123], v[164:167], v[188:191], v[120:123]
	v_mfma_f32_16x16x32_bf16 v[116:119], v[172:175], v[188:191], v[116:119]
	v_mfma_f32_16x16x32_bf16 v[112:115], v[164:167], v[204:207], v[112:115]
	v_mfma_f32_16x16x32_bf16 v[108:111], v[172:175], v[204:207], v[108:111]
	v_mfma_f32_16x16x32_bf16 v[104:107], v[164:167], v[230:233], v[104:107]
	v_mfma_f32_16x16x32_bf16 v[100:103], v[172:175], v[230:233], v[100:103]
	v_mfma_f32_16x16x32_bf16 v[128:131], v[168:171], v[184:187], v[128:131]
	v_mfma_f32_16x16x32_bf16 v[124:127], v[176:179], v[184:187], v[124:127]
	v_mfma_f32_16x16x32_bf16 v[120:123], v[168:171], v[192:195], v[120:123]
	v_mfma_f32_16x16x32_bf16 v[116:119], v[176:179], v[192:195], v[116:119]
	v_mfma_f32_16x16x32_bf16 v[112:115], v[168:171], v[208:211], v[112:115]
	v_mfma_f32_16x16x32_bf16 v[108:111], v[176:179], v[208:211], v[108:111]
	v_mfma_f32_16x16x32_bf16 v[104:107], v[168:171], v[234:237], v[104:107]
	v_mfma_f32_16x16x32_bf16 v[100:103], v[176:179], v[234:237], v[100:103]
	s_barrier
	s_add_i32 s42, s46, s54
	v_lshl_add_u64 v[196:197], v[196:197], 0, s[94:95]
	s_mov_b32 m0, s42
	ds_read_b128 v[180:183], v155 offset:49152
	ds_read_b128 v[184:187], v155 offset:50176
	ds_read_b128 v[188:191], v155 offset:51200
	ds_read_b128 v[192:195], v155 offset:52224
	ds_read_b128 v[204:207], v155 offset:53248
	ds_read_b128 v[208:211], v155 offset:54272
	ds_read_b128 v[230:233], v155 offset:55296
	ds_read_b128 v[234:237], v155 offset:56320
	global_load_lds_dwordx4 v[196:197], off
	s_add_i32 m0, s42, 0x2000
	s_add_u32 s8, s8, 0x100080
	v_lshl_add_u64 v[196:197], v[198:199], 0, s[94:95]
	s_addc_u32 s9, s9, 0
	s_add_i32 s42, s47, s54
	global_load_lds_dwordx4 v[196:197], off
	v_lshl_add_u64 v[196:197], s[8:9], 0, v[136:137]
	s_mov_b32 m0, s42
	s_nop 0
	global_load_lds_dwordx4 v[196:197], off
	v_lshl_add_u64 v[196:197], s[8:9], 0, v[132:133]
	s_add_i32 m0, s42, 0x2000
	s_nop 0
	global_load_lds_dwordx4 v[196:197], off
	v_lshl_add_u64 v[196:197], v[212:213], 0, s[94:95]
	s_mov_b32 m0, s59
	s_nop 0
	global_load_lds_dwordx4 v[196:197], off
	v_lshl_add_u64 v[196:197], v[214:215], 0, s[94:95]
	s_mov_b32 m0, s71
	s_nop 0
	global_load_lds_dwordx4 v[196:197], off
	s_waitcnt vmcnt(8)
	s_waitcnt lgkmcnt(0)
	s_barrier
	v_mfma_f32_16x16x32_bf16 v[32:35], v[144:147], v[180:183], v[32:35]
	v_mfma_f32_16x16x32_bf16 v[28:31], v[156:159], v[180:183], v[28:31]
	v_mfma_f32_16x16x32_bf16 v[24:27], v[144:147], v[188:191], v[24:27]
	v_mfma_f32_16x16x32_bf16 v[20:23], v[156:159], v[188:191], v[20:23]
	v_mfma_f32_16x16x32_bf16 v[16:19], v[144:147], v[204:207], v[16:19]
	v_mfma_f32_16x16x32_bf16 v[12:15], v[156:159], v[204:207], v[12:15]
	v_mfma_f32_16x16x32_bf16 v[8:11], v[144:147], v[230:233], v[8:11]
	v_mfma_f32_16x16x32_bf16 v[4:7], v[156:159], v[230:233], v[4:7]
	v_mfma_f32_16x16x32_bf16 v[32:35], v[148:151], v[184:187], v[32:35]
	v_mfma_f32_16x16x32_bf16 v[28:31], v[160:163], v[184:187], v[28:31]
	v_mfma_f32_16x16x32_bf16 v[24:27], v[148:151], v[192:195], v[24:27]
	v_mfma_f32_16x16x32_bf16 v[20:23], v[160:163], v[192:195], v[20:23]
	v_mfma_f32_16x16x32_bf16 v[16:19], v[148:151], v[208:211], v[16:19]
	v_mfma_f32_16x16x32_bf16 v[12:15], v[160:163], v[208:211], v[12:15]
	v_mfma_f32_16x16x32_bf16 v[8:11], v[148:151], v[234:237], v[8:11]
	v_mfma_f32_16x16x32_bf16 v[4:7], v[160:163], v[234:237], v[4:7]
	v_mfma_f32_16x16x32_bf16 v[96:99], v[164:167], v[180:183], v[96:99]
	v_mfma_f32_16x16x32_bf16 v[92:95], v[172:175], v[180:183], v[92:95]
	v_mfma_f32_16x16x32_bf16 v[88:91], v[164:167], v[188:191], v[88:91]
	v_mfma_f32_16x16x32_bf16 v[84:87], v[172:175], v[188:191], v[84:87]
	v_mfma_f32_16x16x32_bf16 v[80:83], v[164:167], v[204:207], v[80:83]
	v_mfma_f32_16x16x32_bf16 v[76:79], v[172:175], v[204:207], v[76:79]
	v_mfma_f32_16x16x32_bf16 v[72:75], v[164:167], v[230:233], v[72:75]
	v_mfma_f32_16x16x32_bf16 v[68:71], v[172:175], v[230:233], v[68:71]
	v_mfma_f32_16x16x32_bf16 v[96:99], v[168:171], v[184:187], v[96:99]
	v_mfma_f32_16x16x32_bf16 v[92:95], v[176:179], v[184:187], v[92:95]
	v_mfma_f32_16x16x32_bf16 v[88:91], v[168:171], v[192:195], v[88:91]
	v_mfma_f32_16x16x32_bf16 v[84:87], v[176:179], v[192:195], v[84:87]
	v_mfma_f32_16x16x32_bf16 v[80:83], v[168:171], v[208:211], v[80:83]
	v_mfma_f32_16x16x32_bf16 v[76:79], v[176:179], v[208:211], v[76:79]
	v_mfma_f32_16x16x32_bf16 v[72:75], v[168:171], v[234:237], v[72:75]
	v_mfma_f32_16x16x32_bf16 v[68:71], v[176:179], v[234:237], v[68:71]
	s_barrier
	s_add_i32 s45, s45, 2
	s_add_u32 s6, s6, 0x100
	s_addc_u32 s7, s7, 0
	s_add_u32 s40, s40, 0x100
	s_addc_u32 s44, s44, 0
	s_cmp_gt_u32 s45, 61

.LBB0_838:
	s_ashr_i32 s29, s28, 31
	s_lshl_b64 s[10:11], s[28:29], 20
	s_add_u32 s30, s37, s10
	s_addc_u32 s31, s39, s11
	s_and_b64 s[10:11], s[4:5], exec
	s_cselect_b32 s12, s31, s7
	s_cselect_b32 s13, s30, s6
	s_ashr_i32 s27, s26, 31
	s_lshl_b64 s[10:11], s[26:27], 20
	s_add_u32 s34, s14, s10
	s_addc_u32 s35, s36, s11
	s_and_b64 s[10:11], s[4:5], exec
	s_cselect_b32 s27, s35, s9
	s_cselect_b32 s29, s34, s8
	s_add_u32 s6, s6, 0x80080
	s_addc_u32 s7, s7, 0
	s_add_u32 s42, s8, 0x100
	s_addc_u32 s43, s9, 0
	s_mov_b32 s44, -2
	v_and_b32_e32 v250, 63, v0
	v_lshlrev_b32_e32 v250, 2, v250
	s_lshl_b32 s98, s58, 8
	s_add_i32 s98, s98, s57
	s_lshl_b32 s98, s98, 2
	s_add_u32 s98, s24, s98
	s_addc_u32 s99, s25, 0
	s_lshr_b32 m0, s53, 2
	s_sub_i32 m0, s53, m0
	s_add_i32 m0, m0, 0x20000
	s_nop 0
	global_load_lds_dword v250, s[98:99]
	global_load_lds_dword v250, s[98:99] offset:512
	v_and_b32_e32 v251, 31, v0
	v_bfe_u32 v252, v0, 5, 1
	v_lshl_add_u32 v251, v252, 7, v251
	v_lshlrev_b32_e32 v251, 2, v251
	s_mov_b32 s98, s15
	s_lshl_b32 s98, s98, 8
	s_add_i32 s98, s98, s59
	s_lshl_b32 s98, s98, 2
	s_add_u32 s98, s51, s98
	s_addc_u32 s99, s33, 0
	s_add_i32 m0, m0, 0x100
	s_nop 0
	global_load_lds_dword v251, s[98:99]
	s_add_u32 s8, s6, 0xfff80080
	s_addc_u32 s9, s7, -1
	s_add_i32 s45, 0, 0x10000
	s_cmp_eq_u32 s44, 28
	s_cselect_b32 s11, s12, s9
	s_cselect_b32 s10, s13, s8
	v_add_u32_e32 v2, s45, v194
	s_cselect_b32 s9, s27, s43
	s_cselect_b32 s8, s29, s42
	s_add_i32 s62, 0, 0x14000
	ds_read_b128 v[30:33], v2
	ds_read_b128 v[34:37], v2 offset:1024
	ds_read_b128 v[46:49], v2 offset:2048
	ds_read_b128 v[50:53], v2 offset:3072
	v_add_u32_e32 v2, s62, v194
	ds_read_b128 v[162:165], v2
	ds_read_b128 v[166:169], v2 offset:1024
	ds_read_b128 v[170:173], v2 offset:2048
	ds_read_b128 v[174:177], v2 offset:3072
	v_lshl_add_u64 v[4:5], s[6:7], 0, v[158:159]
	s_add_i32 m0, s53, 0xc000
	ds_read_b128 v[178:181], v195
	ds_read_b128 v[182:185], v195 offset:1024
	ds_read_b128 v[186:189], v195 offset:2048
	ds_read_b128 v[204:207], v195 offset:3072
	ds_read_b128 v[208:211], v195 offset:4096
	ds_read_b128 v[230:233], v195 offset:5120
	ds_read_b128 v[234:237], v195 offset:6144
	ds_read_b128 v[238:241], v195 offset:7168
	global_load_lds_dwordx4 v[4:5], off
	v_lshl_add_u64 v[4:5], s[6:7], 0, v[160:161]
	s_add_i32 m0, s53, 0xe000
	s_nop 0
	global_load_lds_dwordx4 v[4:5], off
	s_waitcnt vmcnt(8)
	s_waitcnt lgkmcnt(0)
	s_barrier
	v_mfma_i32_16x16x64_i8 v[146:149], v[30:33], v[178:181], 0
	v_mfma_i32_16x16x64_i8 v[142:145], v[46:49], v[178:181], 0
	v_mfma_i32_16x16x64_i8 v[130:133], v[30:33], v[186:189], 0
	v_mfma_i32_16x16x64_i8 v[126:129], v[46:49], v[186:189], 0
	v_mfma_i32_16x16x64_i8 v[114:117], v[30:33], v[208:211], 0
	v_mfma_i32_16x16x64_i8 v[110:113], v[46:49], v[208:211], 0
	v_mfma_i32_16x16x64_i8 v[98:101], v[30:33], v[234:237], 0
	v_mfma_i32_16x16x64_i8 v[94:97], v[46:49], v[234:237], 0
	v_mfma_i32_16x16x64_i8 v[146:149], v[34:37], v[182:185], v[146:149]
	v_mfma_i32_16x16x64_i8 v[142:145], v[50:53], v[182:185], v[142:145]
	v_mfma_i32_16x16x64_i8 v[130:133], v[34:37], v[204:207], v[130:133]
	v_mfma_i32_16x16x64_i8 v[126:129], v[50:53], v[204:207], v[126:129]
	v_mfma_i32_16x16x64_i8 v[114:117], v[34:37], v[230:233], v[114:117]
	v_mfma_i32_16x16x64_i8 v[110:113], v[50:53], v[230:233], v[110:113]
	v_mfma_i32_16x16x64_i8 v[98:101], v[34:37], v[238:241], v[98:101]
	v_mfma_i32_16x16x64_i8 v[94:97], v[50:53], v[238:241], v[94:97]
	v_mfma_i32_16x16x64_i8 v[138:141], v[162:165], v[178:181], 0
	v_mfma_i32_16x16x64_i8 v[134:137], v[170:173], v[178:181], 0
	v_mfma_i32_16x16x64_i8 v[122:125], v[162:165], v[186:189], 0
	v_mfma_i32_16x16x64_i8 v[118:121], v[170:173], v[186:189], 0
	v_mfma_i32_16x16x64_i8 v[106:109], v[162:165], v[208:211], 0
	v_mfma_i32_16x16x64_i8 v[102:105], v[170:173], v[208:211], 0
	v_mfma_i32_16x16x64_i8 v[90:93], v[162:165], v[234:237], 0
	v_mfma_i32_16x16x64_i8 v[86:89], v[170:173], v[234:237], 0
	v_mfma_i32_16x16x64_i8 v[138:141], v[166:169], v[182:185], v[138:141]
	v_mfma_i32_16x16x64_i8 v[134:137], v[174:177], v[182:185], v[134:137]
	v_mfma_i32_16x16x64_i8 v[122:125], v[166:169], v[204:207], v[122:125]
	v_mfma_i32_16x16x64_i8 v[118:121], v[174:177], v[204:207], v[118:121]
	v_mfma_i32_16x16x64_i8 v[106:109], v[166:169], v[230:233], v[106:109]
	v_mfma_i32_16x16x64_i8 v[102:105], v[174:177], v[230:233], v[102:105]
	v_mfma_i32_16x16x64_i8 v[90:93], v[166:169], v[238:241], v[90:93]
	v_mfma_i32_16x16x64_i8 v[86:89], v[174:177], v[238:241], v[86:89]
	s_barrier
	s_add_i32 s45, s45, s52
	v_lshl_add_u64 v[190:191], s[8:9], 0, v[154:155]
	s_mov_b32 m0, s45
	ds_read_b128 v[178:181], v195 offset:16384
	ds_read_b128 v[182:185], v195 offset:17408
	ds_read_b128 v[186:189], v195 offset:18432
	ds_read_b128 v[204:207], v195 offset:19456
	ds_read_b128 v[208:211], v195 offset:20480
	ds_read_b128 v[230:233], v195 offset:21504
	ds_read_b128 v[234:237], v195 offset:22528
	ds_read_b128 v[238:241], v195 offset:23552
	global_load_lds_dwordx4 v[190:191], off
	s_add_i32 m0, s45, 0x2000
	s_add_u32 s48, s8, 0x80000
	v_lshl_add_u64 v[196:197], s[8:9], 0, v[150:151]
	s_addc_u32 s49, s9, 0
	s_add_i32 s45, s62, s52
	global_load_lds_dwordx4 v[196:197], off
	v_lshl_add_u64 v[4:5], s[48:49], 0, v[154:155]
	s_mov_b32 m0, s45
	v_lshl_add_u64 v[198:199], s[10:11], 0, v[156:157]
	global_load_lds_dwordx4 v[4:5], off
	v_lshl_add_u64 v[4:5], s[48:49], 0, v[150:151]
	s_add_i32 m0, s45, 0x2000
	v_lshl_add_u64 v[212:213], s[10:11], 0, v[152:153]
	global_load_lds_dwordx4 v[4:5], off
	s_mov_b32 m0, s53
	s_nop 0
	global_load_lds_dwordx4 v[198:199], off
	s_mov_b32 m0, s54
	s_nop 0
	global_load_lds_dwordx4 v[212:213], off
	s_waitcnt vmcnt(8)
	s_waitcnt lgkmcnt(0)
	s_barrier
	v_mfma_i32_16x16x64_i8 v[82:85], v[30:33], v[178:181], 0
	v_mfma_i32_16x16x64_i8 v[78:81], v[46:49], v[178:181], 0
	v_mfma_i32_16x16x64_i8 v[66:69], v[30:33], v[186:189], 0
	v_mfma_i32_16x16x64_i8 v[62:65], v[46:49], v[186:189], 0
	v_mfma_i32_16x16x64_i8 v[42:45], v[30:33], v[208:211], 0
	v_mfma_i32_16x16x64_i8 v[38:41], v[46:49], v[208:211], 0
	v_mfma_i32_16x16x64_i8 v[18:21], v[30:33], v[234:237], 0
	v_mfma_i32_16x16x64_i8 v[14:17], v[46:49], v[234:237], 0
	v_mfma_i32_16x16x64_i8 v[82:85], v[34:37], v[182:185], v[82:85]
	v_mfma_i32_16x16x64_i8 v[78:81], v[50:53], v[182:185], v[78:81]
	v_mfma_i32_16x16x64_i8 v[66:69], v[34:37], v[204:207], v[66:69]
	v_mfma_i32_16x16x64_i8 v[62:65], v[50:53], v[204:207], v[62:65]
	v_mfma_i32_16x16x64_i8 v[42:45], v[34:37], v[230:233], v[42:45]
	v_mfma_i32_16x16x64_i8 v[38:41], v[50:53], v[230:233], v[38:41]
	v_mfma_i32_16x16x64_i8 v[18:21], v[34:37], v[238:241], v[18:21]
	v_mfma_i32_16x16x64_i8 v[14:17], v[50:53], v[238:241], v[14:17]
	v_mfma_i32_16x16x64_i8 v[26:29], v[162:165], v[208:211], 0
	v_mfma_i32_16x16x64_i8 v[22:25], v[170:173], v[208:211], 0
	v_mfma_i32_16x16x64_i8 v[10:13], v[162:165], v[234:237], 0
	v_mfma_i32_16x16x64_i8 v[4:7], v[170:173], v[234:237], 0
	v_mfma_i32_16x16x64_i8 v[30:33], v[162:165], v[178:181], 0
	v_mfma_i32_16x16x64_i8 v[34:37], v[170:173], v[178:181], 0
	v_mfma_i32_16x16x64_i8 v[46:49], v[162:165], v[186:189], 0
	v_mfma_i32_16x16x64_i8 v[50:53], v[170:173], v[186:189], 0
	v_mfma_i32_16x16x64_i8 v[26:29], v[166:169], v[230:233], v[26:29]
	v_mfma_i32_16x16x64_i8 v[22:25], v[174:177], v[230:233], v[22:25]
	v_mfma_i32_16x16x64_i8 v[10:13], v[166:169], v[238:241], v[10:13]
	v_mfma_i32_16x16x64_i8 v[4:7], v[174:177], v[238:241], v[4:7]
	v_mfma_i32_16x16x64_i8 v[30:33], v[166:169], v[182:185], v[30:33]
	v_mfma_i32_16x16x64_i8 v[34:37], v[174:177], v[182:185], v[34:37]
	v_mfma_i32_16x16x64_i8 v[46:49], v[166:169], v[204:207], v[46:49]
	v_mfma_i32_16x16x64_i8 v[50:53], v[174:177], v[204:207], v[50:53]
	s_barrier
	s_add_i32 s45, 0, 0x18000
	v_add_u32_e32 v2, s45, v194
	s_add_i32 s48, 0, 0x1c000
	ds_read_b128 v[54:57], v2
	ds_read_b128 v[58:61], v2 offset:1024
	ds_read_b128 v[70:73], v2 offset:2048
	ds_read_b128 v[74:77], v2 offset:3072
	v_add_u32_e32 v2, s48, v194
	ds_read_b128 v[162:165], v2
	ds_read_b128 v[166:169], v2 offset:1024
	ds_read_b128 v[170:173], v2 offset:2048
	ds_read_b128 v[174:177], v2 offset:3072
	s_add_u32 s10, s10, 0x80000
	s_addc_u32 s11, s11, 0
	s_mov_b32 m0, s55
	v_lshl_add_u64 v[8:9], s[10:11], 0, v[156:157]
	ds_read_b128 v[178:181], v195 offset:32768
	ds_read_b128 v[182:185], v195 offset:33792
	ds_read_b128 v[186:189], v195 offset:34816
	ds_read_b128 v[204:207], v195 offset:35840
	ds_read_b128 v[208:211], v195 offset:36864
	ds_read_b128 v[230:233], v195 offset:37888
	ds_read_b128 v[234:237], v195 offset:38912
	ds_read_b128 v[238:241], v195 offset:39936
	global_load_lds_dwordx4 v[8:9], off
	v_lshl_add_u64 v[8:9], s[10:11], 0, v[152:153]
	s_mov_b32 m0, s56
	s_nop 0
	global_load_lds_dwordx4 v[8:9], off
	s_waitcnt vmcnt(8)
	s_waitcnt lgkmcnt(0)
	s_barrier
	v_mfma_i32_16x16x64_i8 v[146:149], v[54:57], v[178:181], v[146:149]
	v_mfma_i32_16x16x64_i8 v[142:145], v[70:73], v[178:181], v[142:145]
	v_mfma_i32_16x16x64_i8 v[130:133], v[54:57], v[186:189], v[130:133]
	v_mfma_i32_16x16x64_i8 v[126:129], v[70:73], v[186:189], v[126:129]
	v_mfma_i32_16x16x64_i8 v[114:117], v[54:57], v[208:211], v[114:117]
	v_mfma_i32_16x16x64_i8 v[110:113], v[70:73], v[208:211], v[110:113]
	v_mfma_i32_16x16x64_i8 v[98:101], v[54:57], v[234:237], v[98:101]
	v_mfma_i32_16x16x64_i8 v[94:97], v[70:73], v[234:237], v[94:97]
	v_mfma_i32_16x16x64_i8 v[146:149], v[58:61], v[182:185], v[146:149]
	v_mfma_i32_16x16x64_i8 v[142:145], v[74:77], v[182:185], v[142:145]
	v_mfma_i32_16x16x64_i8 v[130:133], v[58:61], v[204:207], v[130:133]
	v_mfma_i32_16x16x64_i8 v[126:129], v[74:77], v[204:207], v[126:129]
	v_mfma_i32_16x16x64_i8 v[114:117], v[58:61], v[230:233], v[114:117]
	v_mfma_i32_16x16x64_i8 v[110:113], v[74:77], v[230:233], v[110:113]
	v_mfma_i32_16x16x64_i8 v[98:101], v[58:61], v[238:241], v[98:101]
	v_mfma_i32_16x16x64_i8 v[94:97], v[74:77], v[238:241], v[94:97]
	v_mfma_i32_16x16x64_i8 v[138:141], v[162:165], v[178:181], v[138:141]
	v_mfma_i32_16x16x64_i8 v[134:137], v[170:173], v[178:181], v[134:137]
	v_mfma_i32_16x16x64_i8 v[122:125], v[162:165], v[186:189], v[122:125]
	v_mfma_i32_16x16x64_i8 v[118:121], v[170:173], v[186:189], v[118:121]
	v_mfma_i32_16x16x64_i8 v[106:109], v[162:165], v[208:211], v[106:109]
	v_mfma_i32_16x16x64_i8 v[102:105], v[170:173], v[208:211], v[102:105]
	v_mfma_i32_16x16x64_i8 v[90:93], v[162:165], v[234:237], v[90:93]
	v_mfma_i32_16x16x64_i8 v[86:89], v[170:173], v[234:237], v[86:89]
	v_mfma_i32_16x16x64_i8 v[138:141], v[166:169], v[182:185], v[138:141]
	v_mfma_i32_16x16x64_i8 v[134:137], v[174:177], v[182:185], v[134:137]
	v_mfma_i32_16x16x64_i8 v[122:125], v[166:169], v[204:207], v[122:125]
	v_mfma_i32_16x16x64_i8 v[118:121], v[174:177], v[204:207], v[118:121]
	v_mfma_i32_16x16x64_i8 v[106:109], v[166:169], v[230:233], v[106:109]
	v_mfma_i32_16x16x64_i8 v[102:105], v[174:177], v[230:233], v[102:105]
	v_mfma_i32_16x16x64_i8 v[90:93], v[166:169], v[238:241], v[90:93]
	v_mfma_i32_16x16x64_i8 v[86:89], v[174:177], v[238:241], v[86:89]
	s_barrier
	s_add_i32 s10, s45, s52
	v_lshl_add_u64 v[8:9], v[190:191], 0, s[94:95]
	s_mov_b32 m0, s10
	ds_read_b128 v[178:181], v195 offset:49152
	ds_read_b128 v[182:185], v195 offset:50176
	ds_read_b128 v[186:189], v195 offset:51200
	ds_read_b128 v[204:207], v195 offset:52224
	ds_read_b128 v[208:211], v195 offset:53248
	ds_read_b128 v[230:233], v195 offset:54272
	ds_read_b128 v[234:237], v195 offset:55296
	ds_read_b128 v[238:241], v195 offset:56320
	global_load_lds_dwordx4 v[8:9], off
	s_add_i32 m0, s10, 0x2000
	s_add_u32 s8, s8, 0x80080
	v_lshl_add_u64 v[8:9], v[196:197], 0, s[94:95]
	s_addc_u32 s9, s9, 0
	s_add_i32 s10, s48, s52
	global_load_lds_dwordx4 v[8:9], off
	v_lshl_add_u64 v[8:9], s[8:9], 0, v[154:155]
	s_mov_b32 m0, s10
	s_nop 0
	global_load_lds_dwordx4 v[8:9], off
	v_lshl_add_u64 v[8:9], s[8:9], 0, v[150:151]
	s_add_i32 m0, s10, 0x2000
	s_nop 0
	global_load_lds_dwordx4 v[8:9], off
	v_lshl_add_u64 v[8:9], v[198:199], 0, s[94:95]
	s_mov_b32 m0, s71
	s_nop 0
	global_load_lds_dwordx4 v[8:9], off
	v_lshl_add_u64 v[8:9], v[212:213], 0, s[94:95]
	s_mov_b32 m0, s74
	s_nop 0
	global_load_lds_dwordx4 v[8:9], off
	s_waitcnt vmcnt(8)
	s_waitcnt lgkmcnt(0)
	s_barrier
	v_mfma_i32_16x16x64_i8 v[82:85], v[54:57], v[178:181], v[82:85]
	v_mfma_i32_16x16x64_i8 v[78:81], v[70:73], v[178:181], v[78:81]
	v_mfma_i32_16x16x64_i8 v[66:69], v[54:57], v[186:189], v[66:69]
	v_mfma_i32_16x16x64_i8 v[62:65], v[70:73], v[186:189], v[62:65]
	v_mfma_i32_16x16x64_i8 v[42:45], v[54:57], v[208:211], v[42:45]
	v_mfma_i32_16x16x64_i8 v[38:41], v[70:73], v[208:211], v[38:41]
	v_mfma_i32_16x16x64_i8 v[18:21], v[54:57], v[234:237], v[18:21]
	v_mfma_i32_16x16x64_i8 v[14:17], v[70:73], v[234:237], v[14:17]
	v_mfma_i32_16x16x64_i8 v[82:85], v[58:61], v[182:185], v[82:85]
	v_mfma_i32_16x16x64_i8 v[78:81], v[74:77], v[182:185], v[78:81]
	v_mfma_i32_16x16x64_i8 v[66:69], v[58:61], v[204:207], v[66:69]
	v_mfma_i32_16x16x64_i8 v[62:65], v[74:77], v[204:207], v[62:65]
	v_mfma_i32_16x16x64_i8 v[42:45], v[58:61], v[230:233], v[42:45]
	v_mfma_i32_16x16x64_i8 v[38:41], v[74:77], v[230:233], v[38:41]
	v_mfma_i32_16x16x64_i8 v[18:21], v[58:61], v[238:241], v[18:21]
	v_mfma_i32_16x16x64_i8 v[14:17], v[74:77], v[238:241], v[14:17]
	v_mfma_i32_16x16x64_i8 v[30:33], v[162:165], v[178:181], v[30:33]
	v_mfma_i32_16x16x64_i8 v[74:77], v[166:169], v[182:185], v[30:33]
	v_mfma_i32_16x16x64_i8 v[30:33], v[170:173], v[178:181], v[34:37]
	v_mfma_i32_16x16x64_i8 v[70:73], v[174:177], v[182:185], v[30:33]
	v_mfma_i32_16x16x64_i8 v[30:33], v[162:165], v[186:189], v[46:49]
	v_mfma_i32_16x16x64_i8 v[58:61], v[166:169], v[204:207], v[30:33]
	v_mfma_i32_16x16x64_i8 v[30:33], v[170:173], v[186:189], v[50:53]
	v_mfma_i32_16x16x64_i8 v[26:29], v[162:165], v[208:211], v[26:29]
	v_mfma_i32_16x16x64_i8 v[22:25], v[170:173], v[208:211], v[22:25]
	v_mfma_i32_16x16x64_i8 v[8:11], v[162:165], v[234:237], v[10:13]
	v_mfma_i32_16x16x64_i8 v[4:7], v[170:173], v[234:237], v[4:7]
	v_mfma_i32_16x16x64_i8 v[54:57], v[174:177], v[204:207], v[30:33]
	v_mfma_i32_16x16x64_i8 v[26:29], v[166:169], v[230:233], v[26:29]
	v_mfma_i32_16x16x64_i8 v[22:25], v[174:177], v[230:233], v[22:25]
	v_mfma_i32_16x16x64_i8 v[10:13], v[166:169], v[238:241], v[8:11]
	v_mfma_i32_16x16x64_i8 v[6:9], v[174:177], v[238:241], v[4:7]
	s_barrier
	s_add_i32 s44, s44, 2
	s_add_u32 s6, s6, 0x100
	s_addc_u32 s7, s7, 0
	s_add_u32 s42, s42, 0x100
	s_addc_u32 s43, s43, 0
	s_cmp_gt_u32 s44, 29

.LBB0_842:
	s_lshl_b32 s6, s15, 8
	s_ashr_i32 s7, s6, 31
	v_mov_b32_e32 v165, v193
	v_mov_b32_e32 v167, v192
	s_lshl_b64 s[8:9], s[6:7], 2
	s_add_u32 s8, s51, s8
	v_lshl_add_u32 v4, v165, 3, s59
	s_addc_u32 s9, s33, s9
	v_ashrrev_i32_e32 v5, 31, v4
	s_lshr_b32 m0, s53, 2
	s_sub_i32 m0, s53, m0
	s_nop 0
	v_lshlrev_b32_e32 v34, 5, v165
	v_add_u32_e32 v34, m0, v34
	v_add_u32_e32 v34, 0x20100, v34
	ds_read_b128 v[46:49], v34 offset:16
	ds_read_b128 v[50:53], v34
	ds_read_b128 v[30:33], v34 offset:144
	ds_read_b128 v[34:37], v34 offset:128
	s_cmp_lt_i32 s15, 6
	s_cselect_b64 s[8:9], -1, 0
	s_and_b64 vcc, exec, s[8:9]
	s_cbranch_vccnz .LBB0_864
	s_cmp_gt_u32 s15, 13
	s_mov_b64 s[48:49], -1
	s_cbranch_scc0 .LBB0_866
	s_cmp_eq_u32 s15, 14
	s_mov_b64 s[48:49], 0
	s_cbranch_scc1 .LBB0_865
	s_cmp_gt_u32 s15, 22
	s_mov_b64 s[42:43], -1
	s_cbranch_scc0 .LBB0_862
	s_cmp_gt_u32 s15, 30
	s_cbranch_scc0 .LBB0_859
	s_cmp_gt_u32 s15, 38
	s_cbranch_scc0 .LBB0_856
	s_cmp_gt_u32 s15, 46
	s_cbranch_scc0 .LBB0_853
	s_mov_b64 s[10:11], -1
	s_cmp_gt_u32 s15, 54
	s_mov_b64 s[12:13], -1
	s_cbranch_scc0 .LBB0_851
	s_add_i32 s7, s6, 0xffffc900
	s_mov_b64 s[12:13], 0

.LBB0_869:
	s_lshl_b32 s7, s58, 8
	s_add_i32 s7, s7, s57
	v_add_u32_e32 v162, s7, v167
	v_ashrrev_i32_e32 v163, 31, v162
	s_lshr_b32 m0, s53, 2
	s_sub_i32 m0, s53, m0
	s_nop 0
	v_lshlrev_b32_e32 v180, 2, v167
	v_add_u32_e32 v180, m0, v180
	v_add_u32_e32 v180, 0x20000, v180
	ds_read_b32 v178, v180
	ds_read_b32 v176, v180 offset:64
	ds_read_b32 v174, v180 offset:128
	ds_read_b32 v172, v180 offset:192
	ds_read_b32 v170, v180 offset:512
	ds_read_b32 v168, v180 offset:576
	ds_read_b32 v166, v180 offset:640
	ds_read_b32 v164, v180 offset:704
	v_cvt_f32_i32_e32 v147, v147
	v_cvt_f32_i32_e32 v146, v146
	v_cvt_f32_i32_e32 v143, v143
	v_cvt_f32_i32_e32 v142, v142
	s_xor_b64 s[48:49], s[10:11], -1
	s_mov_b64 s[64:65], -1
	s_mov_b32 s43, s42
	s_and_b64 vcc, exec, s[48:49]
	s_waitcnt lgkmcnt(0)
	v_pk_mul_f32 v[146:147], v[178:179], v[146:147] op_sel_hi:[0,1]
	v_pk_mul_f32 v[142:143], v[178:179], v[142:143] op_sel_hi:[0,1]
	v_pk_mul_f32 v[180:181], v[50:51], v[146:147]
	v_cvt_f32_i32_e32 v147, v149
	v_cvt_f32_i32_e32 v146, v148
	v_pk_mul_f32 v[182:183], v[46:47], v[142:143]
	v_cvt_f32_i32_e32 v143, v145
	v_cvt_f32_i32_e32 v142, v144
	v_pk_mul_f32 v[146:147], v[178:179], v[146:147] op_sel_hi:[0,1]
	v_pk_mul_f32 v[148:149], v[52:53], v[146:147]
	v_pk_mul_f32 v[142:143], v[178:179], v[142:143] op_sel_hi:[0,1]
	v_pk_mul_f32 v[184:185], v[48:49], v[142:143]
	s_cbranch_vccz .LBB0_871
	s_mov_b32 s64, s42
	s_mov_b32 s65, s42
	v_pk_mul_f32 v[188:189], s[64:65], v[148:149]
	v_pk_mul_f32 v[144:145], s[42:43], v[180:181]
	v_pk_mul_f32 v[190:191], s[64:65], v[184:185]
	v_pk_mul_f32 v[142:143], s[42:43], v[182:183]
	s_mov_b64 s[64:65], 0

.LBB0_1150:
	s_add_u32 s49, s28, 0x100
	s_addc_u32 s51, s29, 0
	s_mov_b32 s52, -2
	s_add_u32 s6, s26, 0x100
	s_addc_u32 s7, s27, 0
	s_add_i32 s53, 0, 0x10000
	s_cmp_eq_u32 s52, 20
	s_cselect_b32 s31, s23, s7
	s_cselect_b32 s30, s22, s6
	v_add_u32_e32 v2, s53, v232
	s_cselect_b32 s29, s25, s51
	s_cselect_b32 s28, s24, s49
	s_add_i32 s54, 0, 0x14000
	ds_read_b128 v[108:111], v2
	ds_read_b128 v[112:115], v2 offset:1024
	ds_read_b128 v[120:123], v2 offset:2048
	ds_read_b128 v[128:131], v2 offset:3072
	v_add_u32_e32 v2, s54, v232
	ds_read_b128 v[136:139], v2
	ds_read_b128 v[140:143], v2 offset:1024
	ds_read_b128 v[148:151], v2 offset:2048
	ds_read_b128 v[152:155], v2 offset:3072
	v_lshl_add_u64 v[196:197], s[26:27], 0, v[172:173]
	s_add_i32 m0, s34, 0xc000
	ds_read_b128 v[176:179], v233
	ds_read_b128 v[180:183], v233 offset:1024
	ds_read_b128 v[184:187], v233 offset:2048
	ds_read_b128 v[188:191], v233 offset:3072
	ds_read_b128 v[192:195], v233 offset:4096
	ds_read_b128 v[204:207], v233 offset:5120
	ds_read_b128 v[208:211], v233 offset:6144
	ds_read_b128 v[234:237], v233 offset:7168
	global_load_lds_dwordx4 v[196:197], off
	v_lshl_add_u64 v[196:197], s[26:27], 0, v[174:175]
	s_add_i32 m0, s34, 0xe000
	s_nop 0
	global_load_lds_dwordx4 v[196:197], off
	s_waitcnt vmcnt(8)
	s_waitcnt lgkmcnt(0)
	s_barrier
	v_mfma_f32_16x16x32_bf16 v[160:163], v[108:111], v[176:179], 0
	v_mfma_f32_16x16x32_bf16 v[156:159], v[120:123], v[176:179], 0
	v_mfma_f32_16x16x32_bf16 v[124:127], v[108:111], v[184:187], 0
	v_mfma_f32_16x16x32_bf16 v[116:119], v[120:123], v[184:187], 0
	v_mfma_f32_16x16x32_bf16 v[96:99], v[108:111], v[192:195], 0
	v_mfma_f32_16x16x32_bf16 v[92:95], v[120:123], v[192:195], 0
	v_mfma_f32_16x16x32_bf16 v[80:83], v[108:111], v[208:211], 0
	v_mfma_f32_16x16x32_bf16 v[76:79], v[120:123], v[208:211], 0
	v_mfma_f32_16x16x32_bf16 v[160:163], v[112:115], v[180:183], v[160:163]
	v_mfma_f32_16x16x32_bf16 v[156:159], v[128:131], v[180:183], v[156:159]
	v_mfma_f32_16x16x32_bf16 v[124:127], v[112:115], v[188:191], v[124:127]
	v_mfma_f32_16x16x32_bf16 v[116:119], v[128:131], v[188:191], v[116:119]
	v_mfma_f32_16x16x32_bf16 v[96:99], v[112:115], v[204:207], v[96:99]
	v_mfma_f32_16x16x32_bf16 v[92:95], v[128:131], v[204:207], v[92:95]
	v_mfma_f32_16x16x32_bf16 v[80:83], v[112:115], v[234:237], v[80:83]
	v_mfma_f32_16x16x32_bf16 v[76:79], v[128:131], v[234:237], v[76:79]
	v_mfma_f32_16x16x32_bf16 v[144:147], v[136:139], v[176:179], 0
	v_mfma_f32_16x16x32_bf16 v[132:135], v[148:151], v[176:179], 0
	v_mfma_f32_16x16x32_bf16 v[104:107], v[136:139], v[184:187], 0
	v_mfma_f32_16x16x32_bf16 v[100:103], v[148:151], v[184:187], 0
	v_mfma_f32_16x16x32_bf16 v[88:91], v[136:139], v[192:195], 0
	v_mfma_f32_16x16x32_bf16 v[84:87], v[148:151], v[192:195], 0
	v_mfma_f32_16x16x32_bf16 v[72:75], v[136:139], v[208:211], 0
	v_mfma_f32_16x16x32_bf16 v[68:71], v[148:151], v[208:211], 0
	v_mfma_f32_16x16x32_bf16 v[144:147], v[140:143], v[180:183], v[144:147]
	v_mfma_f32_16x16x32_bf16 v[132:135], v[152:155], v[180:183], v[132:135]
	v_mfma_f32_16x16x32_bf16 v[104:107], v[140:143], v[188:191], v[104:107]
	v_mfma_f32_16x16x32_bf16 v[100:103], v[152:155], v[188:191], v[100:103]
	v_mfma_f32_16x16x32_bf16 v[88:91], v[140:143], v[204:207], v[88:91]
	v_mfma_f32_16x16x32_bf16 v[84:87], v[152:155], v[204:207], v[84:87]
	v_mfma_f32_16x16x32_bf16 v[72:75], v[140:143], v[234:237], v[72:75]
	v_mfma_f32_16x16x32_bf16 v[68:71], v[152:155], v[234:237], v[68:71]
	s_barrier
	s_add_i32 s26, s53, s33
	v_lshl_add_u64 v[196:197], s[28:29], 0, v[168:169]
	s_mov_b32 m0, s26
	ds_read_b128 v[176:179], v233 offset:16384
	ds_read_b128 v[180:183], v233 offset:17408
	ds_read_b128 v[184:187], v233 offset:18432
	ds_read_b128 v[188:191], v233 offset:19456
	ds_read_b128 v[192:195], v233 offset:20480
	ds_read_b128 v[204:207], v233 offset:21504
	ds_read_b128 v[208:211], v233 offset:22528
	ds_read_b128 v[234:237], v233 offset:23552
	global_load_lds_dwordx4 v[196:197], off
	s_add_i32 m0, s26, 0x2000
	s_add_u32 s26, s28, 0x60000
	v_lshl_add_u64 v[198:199], s[28:29], 0, v[164:165]
	s_addc_u32 s27, s29, 0
	s_add_i32 s53, s54, s33
	global_load_lds_dwordx4 v[198:199], off
	v_lshl_add_u64 v[212:213], s[26:27], 0, v[168:169]
	s_mov_b32 m0, s53
	v_lshl_add_u64 v[214:215], s[30:31], 0, v[166:167]
	global_load_lds_dwordx4 v[212:213], off
	v_lshl_add_u64 v[212:213], s[26:27], 0, v[164:165]
	s_add_i32 m0, s53, 0x2000
	s_nop 0
	global_load_lds_dwordx4 v[212:213], off
	v_lshl_add_u64 v[212:213], s[30:31], 0, v[170:171]
	s_mov_b32 m0, s34
	s_nop 0
	global_load_lds_dwordx4 v[212:213], off
	s_mov_b32 m0, s35
	s_nop 0
	global_load_lds_dwordx4 v[214:215], off
	s_waitcnt vmcnt(8)
	s_waitcnt lgkmcnt(0)
	s_barrier
	v_mfma_f32_16x16x32_bf16 v[64:67], v[108:111], v[176:179], 0
	v_mfma_f32_16x16x32_bf16 v[60:63], v[120:123], v[176:179], 0
	v_mfma_f32_16x16x32_bf16 v[48:51], v[108:111], v[184:187], 0
	v_mfma_f32_16x16x32_bf16 v[44:47], v[120:123], v[184:187], 0
	v_mfma_f32_16x16x32_bf16 v[32:35], v[108:111], v[192:195], 0
	v_mfma_f32_16x16x32_bf16 v[28:31], v[120:123], v[192:195], 0
	v_mfma_f32_16x16x32_bf16 v[16:19], v[108:111], v[208:211], 0
	v_mfma_f32_16x16x32_bf16 v[12:15], v[120:123], v[208:211], 0
	v_mfma_f32_16x16x32_bf16 v[64:67], v[112:115], v[180:183], v[64:67]
	v_mfma_f32_16x16x32_bf16 v[60:63], v[128:131], v[180:183], v[60:63]
	v_mfma_f32_16x16x32_bf16 v[48:51], v[112:115], v[188:191], v[48:51]
	v_mfma_f32_16x16x32_bf16 v[44:47], v[128:131], v[188:191], v[44:47]
	v_mfma_f32_16x16x32_bf16 v[32:35], v[112:115], v[204:207], v[32:35]
	v_mfma_f32_16x16x32_bf16 v[28:31], v[128:131], v[204:207], v[28:31]
	v_mfma_f32_16x16x32_bf16 v[16:19], v[112:115], v[234:237], v[16:19]
	v_mfma_f32_16x16x32_bf16 v[12:15], v[128:131], v[234:237], v[12:15]
	v_mfma_f32_16x16x32_bf16 v[56:59], v[136:139], v[176:179], 0
	v_mfma_f32_16x16x32_bf16 v[52:55], v[148:151], v[176:179], 0
	v_mfma_f32_16x16x32_bf16 v[40:43], v[136:139], v[184:187], 0
	v_mfma_f32_16x16x32_bf16 v[36:39], v[148:151], v[184:187], 0
	v_mfma_f32_16x16x32_bf16 v[24:27], v[136:139], v[192:195], 0
	v_mfma_f32_16x16x32_bf16 v[20:23], v[148:151], v[192:195], 0
	v_mfma_f32_16x16x32_bf16 v[8:11], v[136:139], v[208:211], 0
	v_mfma_f32_16x16x32_bf16 v[4:7], v[148:151], v[208:211], 0
	v_mfma_f32_16x16x32_bf16 v[56:59], v[140:143], v[180:183], v[56:59]
	v_mfma_f32_16x16x32_bf16 v[52:55], v[152:155], v[180:183], v[52:55]
	v_mfma_f32_16x16x32_bf16 v[40:43], v[140:143], v[188:191], v[40:43]
	v_mfma_f32_16x16x32_bf16 v[36:39], v[152:155], v[188:191], v[36:39]
	v_mfma_f32_16x16x32_bf16 v[24:27], v[140:143], v[204:207], v[24:27]
	v_mfma_f32_16x16x32_bf16 v[20:23], v[152:155], v[204:207], v[20:23]
	v_mfma_f32_16x16x32_bf16 v[8:11], v[140:143], v[234:237], v[8:11]
	v_mfma_f32_16x16x32_bf16 v[4:7], v[152:155], v[234:237], v[4:7]
	s_barrier
	s_add_i32 s53, 0, 0x18000
	v_add_u32_e32 v2, s53, v232
	s_add_i32 s54, 0, 0x1c000
	ds_read_b128 v[108:111], v2
	ds_read_b128 v[112:115], v2 offset:1024
	ds_read_b128 v[120:123], v2 offset:2048
	ds_read_b128 v[128:131], v2 offset:3072
	v_add_u32_e32 v2, s54, v232
	ds_read_b128 v[136:139], v2
	ds_read_b128 v[140:143], v2 offset:1024
	ds_read_b128 v[148:151], v2 offset:2048
	ds_read_b128 v[152:155], v2 offset:3072
	s_add_u32 s26, s30, 0x60000
	s_addc_u32 s27, s31, 0
	s_mov_b32 m0, s36
	v_lshl_add_u64 v[226:227], s[26:27], 0, v[170:171]
	ds_read_b128 v[176:179], v233 offset:32768
	ds_read_b128 v[180:183], v233 offset:33792
	ds_read_b128 v[184:187], v233 offset:34816
	ds_read_b128 v[188:191], v233 offset:35840
	ds_read_b128 v[192:195], v233 offset:36864
	ds_read_b128 v[204:207], v233 offset:37888
	ds_read_b128 v[208:211], v233 offset:38912
	ds_read_b128 v[234:237], v233 offset:39936
	global_load_lds_dwordx4 v[226:227], off
	v_lshl_add_u64 v[226:227], s[26:27], 0, v[166:167]
	s_mov_b32 m0, s37
	s_nop 0
	global_load_lds_dwordx4 v[226:227], off
	s_waitcnt vmcnt(8)
	s_waitcnt lgkmcnt(0)
	s_barrier
	v_mfma_f32_16x16x32_bf16 v[160:163], v[108:111], v[176:179], v[160:163]
	v_mfma_f32_16x16x32_bf16 v[156:159], v[120:123], v[176:179], v[156:159]
	v_mfma_f32_16x16x32_bf16 v[124:127], v[108:111], v[184:187], v[124:127]
	v_mfma_f32_16x16x32_bf16 v[116:119], v[120:123], v[184:187], v[116:119]
	v_mfma_f32_16x16x32_bf16 v[96:99], v[108:111], v[192:195], v[96:99]
	v_mfma_f32_16x16x32_bf16 v[92:95], v[120:123], v[192:195], v[92:95]
	v_mfma_f32_16x16x32_bf16 v[80:83], v[108:111], v[208:211], v[80:83]
	v_mfma_f32_16x16x32_bf16 v[76:79], v[120:123], v[208:211], v[76:79]
	v_mfma_f32_16x16x32_bf16 v[160:163], v[112:115], v[180:183], v[160:163]
	v_mfma_f32_16x16x32_bf16 v[156:159], v[128:131], v[180:183], v[156:159]
	v_mfma_f32_16x16x32_bf16 v[124:127], v[112:115], v[188:191], v[124:127]
	v_mfma_f32_16x16x32_bf16 v[116:119], v[128:131], v[188:191], v[116:119]
	v_mfma_f32_16x16x32_bf16 v[96:99], v[112:115], v[204:207], v[96:99]
	v_mfma_f32_16x16x32_bf16 v[92:95], v[128:131], v[204:207], v[92:95]
	v_mfma_f32_16x16x32_bf16 v[80:83], v[112:115], v[234:237], v[80:83]
	v_mfma_f32_16x16x32_bf16 v[76:79], v[128:131], v[234:237], v[76:79]
	v_mfma_f32_16x16x32_bf16 v[144:147], v[136:139], v[176:179], v[144:147]
	v_mfma_f32_16x16x32_bf16 v[132:135], v[148:151], v[176:179], v[132:135]
	v_mfma_f32_16x16x32_bf16 v[104:107], v[136:139], v[184:187], v[104:107]
	v_mfma_f32_16x16x32_bf16 v[100:103], v[148:151], v[184:187], v[100:103]
	v_mfma_f32_16x16x32_bf16 v[88:91], v[136:139], v[192:195], v[88:91]
	v_mfma_f32_16x16x32_bf16 v[84:87], v[148:151], v[192:195], v[84:87]
	v_mfma_f32_16x16x32_bf16 v[72:75], v[136:139], v[208:211], v[72:75]
	v_mfma_f32_16x16x32_bf16 v[68:71], v[148:151], v[208:211], v[68:71]
	v_mfma_f32_16x16x32_bf16 v[144:147], v[140:143], v[180:183], v[144:147]
	v_mfma_f32_16x16x32_bf16 v[132:135], v[152:155], v[180:183], v[132:135]
	v_mfma_f32_16x16x32_bf16 v[104:107], v[140:143], v[188:191], v[104:107]
	v_mfma_f32_16x16x32_bf16 v[100:103], v[152:155], v[188:191], v[100:103]
	v_mfma_f32_16x16x32_bf16 v[88:91], v[140:143], v[204:207], v[88:91]
	v_mfma_f32_16x16x32_bf16 v[84:87], v[152:155], v[204:207], v[84:87]
	v_mfma_f32_16x16x32_bf16 v[72:75], v[140:143], v[234:237], v[72:75]
	v_mfma_f32_16x16x32_bf16 v[68:71], v[152:155], v[234:237], v[68:71]
	s_barrier
	s_add_i32 s26, s53, s33
	v_lshl_add_u64 v[196:197], v[196:197], 0, s[94:95]
	s_mov_b32 m0, s26
	ds_read_b128 v[176:179], v233 offset:49152
	ds_read_b128 v[180:183], v233 offset:50176
	ds_read_b128 v[184:187], v233 offset:51200
	ds_read_b128 v[188:191], v233 offset:52224
	ds_read_b128 v[192:195], v233 offset:53248
	ds_read_b128 v[204:207], v233 offset:54272
	ds_read_b128 v[208:211], v233 offset:55296
	ds_read_b128 v[234:237], v233 offset:56320
	global_load_lds_dwordx4 v[196:197], off
	s_add_i32 m0, s26, 0x2000
	s_add_u32 s26, s28, 0x60080
	v_lshl_add_u64 v[196:197], v[198:199], 0, s[94:95]
	s_addc_u32 s27, s29, 0
	s_add_i32 s28, s54, s33
	global_load_lds_dwordx4 v[196:197], off
	v_lshl_add_u64 v[196:197], s[26:27], 0, v[168:169]
	s_mov_b32 m0, s28
	s_nop 0
	global_load_lds_dwordx4 v[196:197], off
	v_lshl_add_u64 v[196:197], s[26:27], 0, v[164:165]
	s_add_i32 m0, s28, 0x2000
	s_nop 0
	global_load_lds_dwordx4 v[196:197], off
	v_lshl_add_u64 v[196:197], v[212:213], 0, s[94:95]
	s_mov_b32 m0, s42
	s_nop 0
	global_load_lds_dwordx4 v[196:197], off
	v_lshl_add_u64 v[196:197], v[214:215], 0, s[94:95]
	s_mov_b32 m0, s43
	s_nop 0
	global_load_lds_dwordx4 v[196:197], off
	s_waitcnt vmcnt(8)
	s_waitcnt lgkmcnt(0)
	s_barrier
	v_mfma_f32_16x16x32_bf16 v[64:67], v[108:111], v[176:179], v[64:67]
	v_mfma_f32_16x16x32_bf16 v[60:63], v[120:123], v[176:179], v[60:63]
	v_mfma_f32_16x16x32_bf16 v[48:51], v[108:111], v[184:187], v[48:51]
	v_mfma_f32_16x16x32_bf16 v[44:47], v[120:123], v[184:187], v[44:47]
	v_mfma_f32_16x16x32_bf16 v[32:35], v[108:111], v[192:195], v[32:35]
	v_mfma_f32_16x16x32_bf16 v[28:31], v[120:123], v[192:195], v[28:31]
	v_mfma_f32_16x16x32_bf16 v[16:19], v[108:111], v[208:211], v[16:19]
	v_mfma_f32_16x16x32_bf16 v[12:15], v[120:123], v[208:211], v[12:15]
	v_mfma_f32_16x16x32_bf16 v[64:67], v[112:115], v[180:183], v[64:67]
	v_mfma_f32_16x16x32_bf16 v[60:63], v[128:131], v[180:183], v[60:63]
	v_mfma_f32_16x16x32_bf16 v[48:51], v[112:115], v[188:191], v[48:51]
	v_mfma_f32_16x16x32_bf16 v[44:47], v[128:131], v[188:191], v[44:47]
	v_mfma_f32_16x16x32_bf16 v[32:35], v[112:115], v[204:207], v[32:35]
	v_mfma_f32_16x16x32_bf16 v[28:31], v[128:131], v[204:207], v[28:31]
	v_mfma_f32_16x16x32_bf16 v[16:19], v[112:115], v[234:237], v[16:19]
	v_mfma_f32_16x16x32_bf16 v[12:15], v[128:131], v[234:237], v[12:15]
	v_mfma_f32_16x16x32_bf16 v[56:59], v[136:139], v[176:179], v[56:59]
	v_mfma_f32_16x16x32_bf16 v[52:55], v[148:151], v[176:179], v[52:55]
	v_mfma_f32_16x16x32_bf16 v[40:43], v[136:139], v[184:187], v[40:43]
	v_mfma_f32_16x16x32_bf16 v[36:39], v[148:151], v[184:187], v[36:39]
	v_mfma_f32_16x16x32_bf16 v[24:27], v[136:139], v[192:195], v[24:27]
	v_mfma_f32_16x16x32_bf16 v[20:23], v[148:151], v[192:195], v[20:23]
	v_mfma_f32_16x16x32_bf16 v[8:11], v[136:139], v[208:211], v[8:11]
	v_mfma_f32_16x16x32_bf16 v[4:7], v[148:151], v[208:211], v[4:7]
	v_mfma_f32_16x16x32_bf16 v[56:59], v[140:143], v[180:183], v[56:59]
	v_mfma_f32_16x16x32_bf16 v[52:55], v[152:155], v[180:183], v[52:55]
	v_mfma_f32_16x16x32_bf16 v[40:43], v[140:143], v[188:191], v[40:43]
	v_mfma_f32_16x16x32_bf16 v[36:39], v[152:155], v[188:191], v[36:39]
	v_mfma_f32_16x16x32_bf16 v[24:27], v[140:143], v[204:207], v[24:27]
	v_mfma_f32_16x16x32_bf16 v[20:23], v[152:155], v[204:207], v[20:23]
	v_mfma_f32_16x16x32_bf16 v[8:11], v[140:143], v[234:237], v[8:11]
	v_mfma_f32_16x16x32_bf16 v[4:7], v[152:155], v[234:237], v[4:7]
	s_barrier
	s_add_i32 s52, s52, 2
	s_add_u32 s49, s49, 0x100
	s_addc_u32 s51, s51, 0
	s_cmp_gt_u32 s52, 21
	s_mov_b64 s[26:27], s[6:7]

.LBB0_1202:
	s_ashr_i32 s19, s18, 31
	s_lshl_b64 s[20:21], s[18:19], 18
	s_add_u32 s20, s0, s20
	s_addc_u32 s21, s1, s21
	s_and_b64 s[22:23], s[4:5], exec
	s_cselect_b32 s19, s21, s25
	s_cselect_b32 s45, s20, s24
	s_ashr_i32 s17, s16, 31
	s_lshl_b64 s[22:23], s[16:17], 18
	s_add_u32 s22, s14, s22
	s_addc_u32 s23, s15, s23
	s_and_b64 s[28:29], s[4:5], exec
	s_cselect_b32 s17, s23, s27
	s_cselect_b32 s46, s22, s26
	s_add_u32 s24, s24, 0x20080
	s_addc_u32 s25, s25, 0
	s_add_u32 s47, s26, 0x100
	s_addc_u32 s48, s27, 0
	s_mov_b32 s49, -2
	s_add_u32 s26, s24, 0xfffe0080
	s_addc_u32 s27, s25, -1
	s_add_i32 s51, 0, 0x10000
	s_cmp_eq_u32 s49, 4
	s_cselect_b32 s29, s19, s27
	s_cselect_b32 s28, s45, s26
	v_add_u32_e32 v154, s51, v158
	s_cselect_b32 s27, s17, s48
	s_cselect_b32 s26, s46, s47
	s_add_i32 s54, 0, 0x14000
	ds_read_b128 v[142:145], v154
	ds_read_b128 v[146:149], v154 offset:1024
	ds_read_b128 v[150:153], v154 offset:2048
	ds_read_b128 v[160:163], v154 offset:3072
	v_add_u32_e32 v154, s54, v158
	ds_read_b128 v[164:167], v154
	ds_read_b128 v[168:171], v154 offset:1024
	ds_read_b128 v[172:175], v154 offset:2048
	ds_read_b128 v[176:179], v154 offset:3072
	v_lshl_add_u64 v[154:155], s[24:25], 0, v[138:139]
	s_add_i32 m0, s31, 0xc000
	ds_read_b128 v[180:183], v159
	ds_read_b128 v[184:187], v159 offset:1024
	ds_read_b128 v[188:191], v159 offset:2048
	ds_read_b128 v[192:195], v159 offset:3072
	ds_read_b128 v[204:207], v159 offset:4096
	ds_read_b128 v[208:211], v159 offset:5120
	ds_read_b128 v[230:233], v159 offset:6144
	ds_read_b128 v[234:237], v159 offset:7168
	global_load_lds_dwordx4 v[154:155], off
	v_lshl_add_u64 v[154:155], s[24:25], 0, v[140:141]
	s_add_i32 m0, s31, 0xe000
	s_nop 0
	global_load_lds_dwordx4 v[154:155], off
	s_waitcnt vmcnt(8)
	s_waitcnt lgkmcnt(0)
	s_barrier
	v_mfma_f32_16x16x32_bf16 v[128:131], v[142:145], v[180:183], 0
	v_mfma_f32_16x16x32_bf16 v[124:127], v[150:153], v[180:183], 0
	v_mfma_f32_16x16x32_bf16 v[112:115], v[142:145], v[188:191], 0
	v_mfma_f32_16x16x32_bf16 v[108:111], v[150:153], v[188:191], 0
	v_mfma_f32_16x16x32_bf16 v[96:99], v[142:145], v[204:207], 0
	v_mfma_f32_16x16x32_bf16 v[92:95], v[150:153], v[204:207], 0
	v_mfma_f32_16x16x32_bf16 v[80:83], v[142:145], v[230:233], 0
	v_mfma_f32_16x16x32_bf16 v[76:79], v[150:153], v[230:233], 0
	v_mfma_f32_16x16x32_bf16 v[128:131], v[146:149], v[184:187], v[128:131]
	v_mfma_f32_16x16x32_bf16 v[124:127], v[160:163], v[184:187], v[124:127]
	v_mfma_f32_16x16x32_bf16 v[112:115], v[146:149], v[192:195], v[112:115]
	v_mfma_f32_16x16x32_bf16 v[108:111], v[160:163], v[192:195], v[108:111]
	v_mfma_f32_16x16x32_bf16 v[96:99], v[146:149], v[208:211], v[96:99]
	v_mfma_f32_16x16x32_bf16 v[92:95], v[160:163], v[208:211], v[92:95]
	v_mfma_f32_16x16x32_bf16 v[80:83], v[146:149], v[234:237], v[80:83]
	v_mfma_f32_16x16x32_bf16 v[76:79], v[160:163], v[234:237], v[76:79]
	v_mfma_f32_16x16x32_bf16 v[120:123], v[164:167], v[180:183], 0
	v_mfma_f32_16x16x32_bf16 v[116:119], v[172:175], v[180:183], 0
	v_mfma_f32_16x16x32_bf16 v[104:107], v[164:167], v[188:191], 0
	v_mfma_f32_16x16x32_bf16 v[100:103], v[172:175], v[188:191], 0
	v_mfma_f32_16x16x32_bf16 v[88:91], v[164:167], v[204:207], 0
	v_mfma_f32_16x16x32_bf16 v[84:87], v[172:175], v[204:207], 0
	v_mfma_f32_16x16x32_bf16 v[72:75], v[164:167], v[230:233], 0
	v_mfma_f32_16x16x32_bf16 v[68:71], v[172:175], v[230:233], 0
	v_mfma_f32_16x16x32_bf16 v[120:123], v[168:171], v[184:187], v[120:123]
	v_mfma_f32_16x16x32_bf16 v[116:119], v[176:179], v[184:187], v[116:119]
	v_mfma_f32_16x16x32_bf16 v[104:107], v[168:171], v[192:195], v[104:107]
	v_mfma_f32_16x16x32_bf16 v[100:103], v[176:179], v[192:195], v[100:103]
	v_mfma_f32_16x16x32_bf16 v[88:91], v[168:171], v[208:211], v[88:91]
	v_mfma_f32_16x16x32_bf16 v[84:87], v[176:179], v[208:211], v[84:87]
	v_mfma_f32_16x16x32_bf16 v[72:75], v[168:171], v[234:237], v[72:75]
	v_mfma_f32_16x16x32_bf16 v[68:71], v[176:179], v[234:237], v[68:71]
	s_barrier
	s_add_i32 s51, s51, s30
	v_lshl_add_u64 v[154:155], s[26:27], 0, v[2:3]
	s_mov_b32 m0, s51
	ds_read_b128 v[180:183], v159 offset:16384
	ds_read_b128 v[184:187], v159 offset:17408
	ds_read_b128 v[188:191], v159 offset:18432
	ds_read_b128 v[192:195], v159 offset:19456
	ds_read_b128 v[204:207], v159 offset:20480
	ds_read_b128 v[208:211], v159 offset:21504
	ds_read_b128 v[230:233], v159 offset:22528
	ds_read_b128 v[234:237], v159 offset:23552
	global_load_lds_dwordx4 v[154:155], off
	s_add_i32 m0, s51, 0x2000
	s_add_u32 s52, s26, 0x20000
	v_lshl_add_u64 v[196:197], s[26:27], 0, v[132:133]
	s_addc_u32 s53, s27, 0
	s_add_i32 s51, s54, s30
	global_load_lds_dwordx4 v[196:197], off
	v_lshl_add_u64 v[198:199], s[52:53], 0, v[2:3]
	s_mov_b32 m0, s51
	v_lshl_add_u64 v[212:213], s[28:29], 0, v[134:135]
	global_load_lds_dwordx4 v[198:199], off
	v_lshl_add_u64 v[198:199], s[52:53], 0, v[132:133]
	s_add_i32 m0, s51, 0x2000
	s_nop 0
	global_load_lds_dwordx4 v[198:199], off
	v_lshl_add_u64 v[198:199], s[28:29], 0, v[136:137]
	s_mov_b32 m0, s31
	s_nop 0
	global_load_lds_dwordx4 v[198:199], off
	s_mov_b32 m0, s33
	s_nop 0
	global_load_lds_dwordx4 v[212:213], off
	s_waitcnt vmcnt(8)
	s_waitcnt lgkmcnt(0)
	s_barrier
	v_mfma_f32_16x16x32_bf16 v[64:67], v[142:145], v[180:183], 0
	v_mfma_f32_16x16x32_bf16 v[60:63], v[150:153], v[180:183], 0
	v_mfma_f32_16x16x32_bf16 v[48:51], v[142:145], v[188:191], 0
	v_mfma_f32_16x16x32_bf16 v[44:47], v[150:153], v[188:191], 0
	v_mfma_f32_16x16x32_bf16 v[32:35], v[142:145], v[204:207], 0
	v_mfma_f32_16x16x32_bf16 v[28:31], v[150:153], v[204:207], 0
	v_mfma_f32_16x16x32_bf16 v[16:19], v[142:145], v[230:233], 0
	v_mfma_f32_16x16x32_bf16 v[12:15], v[150:153], v[230:233], 0
	v_mfma_f32_16x16x32_bf16 v[64:67], v[146:149], v[184:187], v[64:67]
	v_mfma_f32_16x16x32_bf16 v[60:63], v[160:163], v[184:187], v[60:63]
	v_mfma_f32_16x16x32_bf16 v[48:51], v[146:149], v[192:195], v[48:51]
	v_mfma_f32_16x16x32_bf16 v[44:47], v[160:163], v[192:195], v[44:47]
	v_mfma_f32_16x16x32_bf16 v[32:35], v[146:149], v[208:211], v[32:35]
	v_mfma_f32_16x16x32_bf16 v[28:31], v[160:163], v[208:211], v[28:31]
	v_mfma_f32_16x16x32_bf16 v[16:19], v[146:149], v[234:237], v[16:19]
	v_mfma_f32_16x16x32_bf16 v[12:15], v[160:163], v[234:237], v[12:15]
	v_mfma_f32_16x16x32_bf16 v[56:59], v[164:167], v[180:183], 0
	v_mfma_f32_16x16x32_bf16 v[52:55], v[172:175], v[180:183], 0
	v_mfma_f32_16x16x32_bf16 v[40:43], v[164:167], v[188:191], 0
	v_mfma_f32_16x16x32_bf16 v[36:39], v[172:175], v[188:191], 0
	v_mfma_f32_16x16x32_bf16 v[24:27], v[164:167], v[204:207], 0
	v_mfma_f32_16x16x32_bf16 v[20:23], v[172:175], v[204:207], 0
	v_mfma_f32_16x16x32_bf16 v[8:11], v[164:167], v[230:233], 0
	v_mfma_f32_16x16x32_bf16 v[4:7], v[172:175], v[230:233], 0
	v_mfma_f32_16x16x32_bf16 v[56:59], v[168:171], v[184:187], v[56:59]
	v_mfma_f32_16x16x32_bf16 v[52:55], v[176:179], v[184:187], v[52:55]
	v_mfma_f32_16x16x32_bf16 v[40:43], v[168:171], v[192:195], v[40:43]
	v_mfma_f32_16x16x32_bf16 v[36:39], v[176:179], v[192:195], v[36:39]
	v_mfma_f32_16x16x32_bf16 v[24:27], v[168:171], v[208:211], v[24:27]
	v_mfma_f32_16x16x32_bf16 v[20:23], v[176:179], v[208:211], v[20:23]
	v_mfma_f32_16x16x32_bf16 v[8:11], v[168:171], v[234:237], v[8:11]
	v_mfma_f32_16x16x32_bf16 v[4:7], v[176:179], v[234:237], v[4:7]
	s_barrier
	s_add_i32 s51, 0, 0x18000
	s_add_i32 s52, 0, 0x1c000
	v_add_u32_e32 v160, s51, v158
	v_add_u32_e32 v176, s52, v158
	ds_read_b128 v[142:145], v160
	ds_read_b128 v[146:149], v160 offset:1024
	ds_read_b128 v[150:153], v160 offset:2048
	ds_read_b128 v[160:163], v160 offset:3072
	ds_read_b128 v[164:167], v176
	ds_read_b128 v[168:171], v176 offset:1024
	ds_read_b128 v[172:175], v176 offset:2048
	ds_read_b128 v[176:179], v176 offset:3072
	s_add_u32 s28, s28, 0x20000
	s_addc_u32 s29, s29, 0
	s_mov_b32 m0, s34
	v_lshl_add_u64 v[214:215], s[28:29], 0, v[136:137]
	ds_read_b128 v[180:183], v159 offset:32768
	ds_read_b128 v[184:187], v159 offset:33792
	ds_read_b128 v[188:191], v159 offset:34816
	ds_read_b128 v[192:195], v159 offset:35840
	ds_read_b128 v[204:207], v159 offset:36864
	ds_read_b128 v[208:211], v159 offset:37888
	ds_read_b128 v[230:233], v159 offset:38912
	ds_read_b128 v[234:237], v159 offset:39936
	global_load_lds_dwordx4 v[214:215], off
	v_lshl_add_u64 v[214:215], s[28:29], 0, v[134:135]
	s_mov_b32 m0, s35
	s_nop 0
	global_load_lds_dwordx4 v[214:215], off
	s_waitcnt vmcnt(8)
	s_waitcnt lgkmcnt(0)
	s_barrier
	v_mfma_f32_16x16x32_bf16 v[128:131], v[142:145], v[180:183], v[128:131]
	v_mfma_f32_16x16x32_bf16 v[124:127], v[150:153], v[180:183], v[124:127]
	v_mfma_f32_16x16x32_bf16 v[112:115], v[142:145], v[188:191], v[112:115]
	v_mfma_f32_16x16x32_bf16 v[108:111], v[150:153], v[188:191], v[108:111]
	v_mfma_f32_16x16x32_bf16 v[96:99], v[142:145], v[204:207], v[96:99]
	v_mfma_f32_16x16x32_bf16 v[92:95], v[150:153], v[204:207], v[92:95]
	v_mfma_f32_16x16x32_bf16 v[80:83], v[142:145], v[230:233], v[80:83]
	v_mfma_f32_16x16x32_bf16 v[76:79], v[150:153], v[230:233], v[76:79]
	v_mfma_f32_16x16x32_bf16 v[128:131], v[146:149], v[184:187], v[128:131]
	v_mfma_f32_16x16x32_bf16 v[124:127], v[160:163], v[184:187], v[124:127]
	v_mfma_f32_16x16x32_bf16 v[112:115], v[146:149], v[192:195], v[112:115]
	v_mfma_f32_16x16x32_bf16 v[108:111], v[160:163], v[192:195], v[108:111]
	v_mfma_f32_16x16x32_bf16 v[96:99], v[146:149], v[208:211], v[96:99]
	v_mfma_f32_16x16x32_bf16 v[92:95], v[160:163], v[208:211], v[92:95]
	v_mfma_f32_16x16x32_bf16 v[80:83], v[146:149], v[234:237], v[80:83]
	v_mfma_f32_16x16x32_bf16 v[76:79], v[160:163], v[234:237], v[76:79]
	v_mfma_f32_16x16x32_bf16 v[120:123], v[164:167], v[180:183], v[120:123]
	v_mfma_f32_16x16x32_bf16 v[116:119], v[172:175], v[180:183], v[116:119]
	v_mfma_f32_16x16x32_bf16 v[104:107], v[164:167], v[188:191], v[104:107]
	v_mfma_f32_16x16x32_bf16 v[100:103], v[172:175], v[188:191], v[100:103]
	v_mfma_f32_16x16x32_bf16 v[88:91], v[164:167], v[204:207], v[88:91]
	v_mfma_f32_16x16x32_bf16 v[84:87], v[172:175], v[204:207], v[84:87]
	v_mfma_f32_16x16x32_bf16 v[72:75], v[164:167], v[230:233], v[72:75]
	v_mfma_f32_16x16x32_bf16 v[68:71], v[172:175], v[230:233], v[68:71]
	v_mfma_f32_16x16x32_bf16 v[120:123], v[168:171], v[184:187], v[120:123]
	v_mfma_f32_16x16x32_bf16 v[116:119], v[176:179], v[184:187], v[116:119]
	v_mfma_f32_16x16x32_bf16 v[104:107], v[168:171], v[192:195], v[104:107]
	v_mfma_f32_16x16x32_bf16 v[100:103], v[176:179], v[192:195], v[100:103]
	v_mfma_f32_16x16x32_bf16 v[88:91], v[168:171], v[208:211], v[88:91]
	v_mfma_f32_16x16x32_bf16 v[84:87], v[176:179], v[208:211], v[84:87]
	v_mfma_f32_16x16x32_bf16 v[72:75], v[168:171], v[234:237], v[72:75]
	v_mfma_f32_16x16x32_bf16 v[68:71], v[176:179], v[234:237], v[68:71]
	s_barrier
	s_add_i32 s28, s51, s30
	v_lshl_add_u64 v[154:155], v[154:155], 0, s[94:95]
	s_mov_b32 m0, s28
	ds_read_b128 v[180:183], v159 offset:49152
	ds_read_b128 v[184:187], v159 offset:50176
	ds_read_b128 v[188:191], v159 offset:51200
	ds_read_b128 v[192:195], v159 offset:52224
	ds_read_b128 v[204:207], v159 offset:53248
	ds_read_b128 v[208:211], v159 offset:54272
	ds_read_b128 v[230:233], v159 offset:55296
	ds_read_b128 v[234:237], v159 offset:56320
	global_load_lds_dwordx4 v[154:155], off
	s_add_i32 m0, s28, 0x2000
	s_add_u32 s26, s26, 0x20080
	v_lshl_add_u64 v[154:155], v[196:197], 0, s[94:95]
	s_addc_u32 s27, s27, 0
	s_add_i32 s28, s52, s30
	global_load_lds_dwordx4 v[154:155], off
	v_lshl_add_u64 v[154:155], s[26:27], 0, v[2:3]
	s_mov_b32 m0, s28
	s_nop 0
	global_load_lds_dwordx4 v[154:155], off
	v_lshl_add_u64 v[154:155], s[26:27], 0, v[132:133]
	s_add_i32 m0, s28, 0x2000
	s_nop 0
	global_load_lds_dwordx4 v[154:155], off
	v_lshl_add_u64 v[154:155], v[198:199], 0, s[94:95]
	s_mov_b32 m0, s39
	s_nop 0
	global_load_lds_dwordx4 v[154:155], off
	v_lshl_add_u64 v[154:155], v[212:213], 0, s[94:95]
	s_mov_b32 m0, s40
	s_nop 0
	global_load_lds_dwordx4 v[154:155], off
	s_waitcnt vmcnt(8)
	s_waitcnt lgkmcnt(0)
	s_barrier
	v_mfma_f32_16x16x32_bf16 v[64:67], v[142:145], v[180:183], v[64:67]
	v_mfma_f32_16x16x32_bf16 v[60:63], v[150:153], v[180:183], v[60:63]
	v_mfma_f32_16x16x32_bf16 v[48:51], v[142:145], v[188:191], v[48:51]
	v_mfma_f32_16x16x32_bf16 v[44:47], v[150:153], v[188:191], v[44:47]
	v_mfma_f32_16x16x32_bf16 v[32:35], v[142:145], v[204:207], v[32:35]
	v_mfma_f32_16x16x32_bf16 v[28:31], v[150:153], v[204:207], v[28:31]
	v_mfma_f32_16x16x32_bf16 v[16:19], v[142:145], v[230:233], v[16:19]
	v_mfma_f32_16x16x32_bf16 v[12:15], v[150:153], v[230:233], v[12:15]
	v_mfma_f32_16x16x32_bf16 v[64:67], v[146:149], v[184:187], v[64:67]
	v_mfma_f32_16x16x32_bf16 v[60:63], v[160:163], v[184:187], v[60:63]
	v_mfma_f32_16x16x32_bf16 v[48:51], v[146:149], v[192:195], v[48:51]
	v_mfma_f32_16x16x32_bf16 v[44:47], v[160:163], v[192:195], v[44:47]
	v_mfma_f32_16x16x32_bf16 v[32:35], v[146:149], v[208:211], v[32:35]
	v_mfma_f32_16x16x32_bf16 v[28:31], v[160:163], v[208:211], v[28:31]
	v_mfma_f32_16x16x32_bf16 v[16:19], v[146:149], v[234:237], v[16:19]
	v_mfma_f32_16x16x32_bf16 v[12:15], v[160:163], v[234:237], v[12:15]
	v_mfma_f32_16x16x32_bf16 v[56:59], v[164:167], v[180:183], v[56:59]
	v_mfma_f32_16x16x32_bf16 v[52:55], v[172:175], v[180:183], v[52:55]
	v_mfma_f32_16x16x32_bf16 v[40:43], v[164:167], v[188:191], v[40:43]
	v_mfma_f32_16x16x32_bf16 v[36:39], v[172:175], v[188:191], v[36:39]
	v_mfma_f32_16x16x32_bf16 v[24:27], v[164:167], v[204:207], v[24:27]
	v_mfma_f32_16x16x32_bf16 v[20:23], v[172:175], v[204:207], v[20:23]
	v_mfma_f32_16x16x32_bf16 v[8:11], v[164:167], v[230:233], v[8:11]
	v_mfma_f32_16x16x32_bf16 v[4:7], v[172:175], v[230:233], v[4:7]
	v_mfma_f32_16x16x32_bf16 v[56:59], v[168:171], v[184:187], v[56:59]
	v_mfma_f32_16x16x32_bf16 v[52:55], v[176:179], v[184:187], v[52:55]
	v_mfma_f32_16x16x32_bf16 v[40:43], v[168:171], v[192:195], v[40:43]
	v_mfma_f32_16x16x32_bf16 v[36:39], v[176:179], v[192:195], v[36:39]
	v_mfma_f32_16x16x32_bf16 v[24:27], v[168:171], v[208:211], v[24:27]
	v_mfma_f32_16x16x32_bf16 v[20:23], v[176:179], v[208:211], v[20:23]
	v_mfma_f32_16x16x32_bf16 v[8:11], v[168:171], v[234:237], v[8:11]
	v_mfma_f32_16x16x32_bf16 v[4:7], v[176:179], v[234:237], v[4:7]
	s_barrier
	s_add_i32 s49, s49, 2
	s_add_u32 s24, s24, 0x100
	s_addc_u32 s25, s25, 0
	s_add_u32 s47, s47, 0x100
	s_addc_u32 s48, s48, 0
	s_cmp_gt_u32 s49, 5

.LBB0_3455:
	s_ashr_i32 s29, s28, 31
	s_lshl_b64 s[10:11], s[28:29], 20
	s_add_u32 s30, s14, s10
	s_addc_u32 s31, s39, s11
	s_and_b64 s[10:11], s[4:5], exec
	s_cselect_b32 s12, s31, s7
	s_cselect_b32 s13, s30, s6
	s_ashr_i32 s27, s26, 31
	s_lshl_b64 s[10:11], s[26:27], 20
	s_add_u32 s34, s52, s10
	s_addc_u32 s35, s53, s11
	s_and_b64 s[10:11], s[4:5], exec
	s_cselect_b32 s27, s35, s9
	s_cselect_b32 s29, s34, s8
	s_add_u32 s6, s6, 0x80080
	s_addc_u32 s7, s7, 0
	s_add_u32 s36, s8, 0x100
	s_addc_u32 s37, s9, 0
	s_mov_b32 s42, -2
	v_and_b32_e32 v250, 63, v0
	v_lshlrev_b32_e32 v250, 2, v250
	s_lshl_b32 s98, s58, 8
	s_add_i32 s98, s98, s64
	s_lshl_b32 s98, s98, 2
	s_add_u32 s98, s24, s98
	s_addc_u32 s99, s25, 0
	s_lshr_b32 m0, s55, 2
	s_sub_i32 m0, s55, m0
	s_add_i32 m0, m0, 0x20000
	s_nop 0
	global_load_lds_dword v250, s[98:99]
	global_load_lds_dword v250, s[98:99] offset:512
	v_and_b32_e32 v251, 31, v0
	v_bfe_u32 v252, v0, 5, 1
	v_lshl_add_u32 v251, v252, 7, v251
	v_lshlrev_b32_e32 v251, 2, v251
	s_add_i32 s98, s15, 55
	s_lshl_b32 s98, s98, 8
	s_add_i32 s98, s98, s65
	s_lshl_b32 s98, s98, 2
	s_add_u32 s98, s51, s98
	s_addc_u32 s99, s33, 0
	s_add_i32 m0, m0, 0x100
	s_nop 0
	global_load_lds_dword v251, s[98:99]
	s_add_u32 s8, s6, 0xfff80080
	s_addc_u32 s9, s7, -1
	s_add_i32 s43, 0, 0x10000
	s_cmp_eq_u32 s42, 28
	s_cselect_b32 s11, s12, s9
	s_cselect_b32 s10, s13, s8
	v_add_u32_e32 v2, s43, v194
	s_cselect_b32 s9, s27, s37
	s_cselect_b32 s8, s29, s36
	s_add_i32 s48, 0, 0x14000
	ds_read_b128 v[30:33], v2
	ds_read_b128 v[34:37], v2 offset:1024
	ds_read_b128 v[46:49], v2 offset:2048
	ds_read_b128 v[50:53], v2 offset:3072
	v_add_u32_e32 v2, s48, v194
	ds_read_b128 v[162:165], v2
	ds_read_b128 v[166:169], v2 offset:1024
	ds_read_b128 v[170:173], v2 offset:2048
	ds_read_b128 v[174:177], v2 offset:3072
	v_lshl_add_u64 v[4:5], s[6:7], 0, v[158:159]
	s_add_i32 m0, s55, 0xc000
	ds_read_b128 v[178:181], v195
	ds_read_b128 v[182:185], v195 offset:1024
	ds_read_b128 v[186:189], v195 offset:2048
	ds_read_b128 v[196:199], v195 offset:3072
	ds_read_b128 v[204:207], v195 offset:4096
	ds_read_b128 v[208:211], v195 offset:5120
	ds_read_b128 v[212:215], v195 offset:6144
	ds_read_b128 v[226:229], v195 offset:7168
	global_load_lds_dwordx4 v[4:5], off
	v_lshl_add_u64 v[4:5], s[6:7], 0, v[160:161]
	s_add_i32 m0, s55, 0xe000
	s_nop 0
	global_load_lds_dwordx4 v[4:5], off
	s_waitcnt vmcnt(8)
	s_waitcnt lgkmcnt(0)
	s_barrier
	v_mfma_i32_16x16x64_i8 v[146:149], v[30:33], v[178:181], 0
	v_mfma_i32_16x16x64_i8 v[142:145], v[46:49], v[178:181], 0
	v_mfma_i32_16x16x64_i8 v[130:133], v[30:33], v[186:189], 0
	v_mfma_i32_16x16x64_i8 v[126:129], v[46:49], v[186:189], 0
	v_mfma_i32_16x16x64_i8 v[114:117], v[30:33], v[204:207], 0
	v_mfma_i32_16x16x64_i8 v[110:113], v[46:49], v[204:207], 0
	v_mfma_i32_16x16x64_i8 v[98:101], v[30:33], v[212:215], 0
	v_mfma_i32_16x16x64_i8 v[94:97], v[46:49], v[212:215], 0
	v_mfma_i32_16x16x64_i8 v[146:149], v[34:37], v[182:185], v[146:149]
	v_mfma_i32_16x16x64_i8 v[142:145], v[50:53], v[182:185], v[142:145]
	v_mfma_i32_16x16x64_i8 v[130:133], v[34:37], v[196:199], v[130:133]
	v_mfma_i32_16x16x64_i8 v[126:129], v[50:53], v[196:199], v[126:129]
	v_mfma_i32_16x16x64_i8 v[114:117], v[34:37], v[208:211], v[114:117]
	v_mfma_i32_16x16x64_i8 v[110:113], v[50:53], v[208:211], v[110:113]
	v_mfma_i32_16x16x64_i8 v[98:101], v[34:37], v[226:229], v[98:101]
	v_mfma_i32_16x16x64_i8 v[94:97], v[50:53], v[226:229], v[94:97]
	v_mfma_i32_16x16x64_i8 v[138:141], v[162:165], v[178:181], 0
	v_mfma_i32_16x16x64_i8 v[134:137], v[170:173], v[178:181], 0
	v_mfma_i32_16x16x64_i8 v[122:125], v[162:165], v[186:189], 0
	v_mfma_i32_16x16x64_i8 v[118:121], v[170:173], v[186:189], 0
	v_mfma_i32_16x16x64_i8 v[106:109], v[162:165], v[204:207], 0
	v_mfma_i32_16x16x64_i8 v[102:105], v[170:173], v[204:207], 0
	v_mfma_i32_16x16x64_i8 v[90:93], v[162:165], v[212:215], 0
	v_mfma_i32_16x16x64_i8 v[86:89], v[170:173], v[212:215], 0
	v_mfma_i32_16x16x64_i8 v[138:141], v[166:169], v[182:185], v[138:141]
	v_mfma_i32_16x16x64_i8 v[134:137], v[174:177], v[182:185], v[134:137]
	v_mfma_i32_16x16x64_i8 v[122:125], v[166:169], v[196:199], v[122:125]
	v_mfma_i32_16x16x64_i8 v[118:121], v[174:177], v[196:199], v[118:121]
	v_mfma_i32_16x16x64_i8 v[106:109], v[166:169], v[208:211], v[106:109]
	v_mfma_i32_16x16x64_i8 v[102:105], v[174:177], v[208:211], v[102:105]
	v_mfma_i32_16x16x64_i8 v[90:93], v[166:169], v[226:229], v[90:93]
	v_mfma_i32_16x16x64_i8 v[86:89], v[174:177], v[226:229], v[86:89]
	s_barrier
	s_add_i32 s43, s43, s54
	v_lshl_add_u64 v[190:191], s[8:9], 0, v[154:155]
	s_mov_b32 m0, s43
	ds_read_b128 v[178:181], v195 offset:16384
	ds_read_b128 v[182:185], v195 offset:17408
	ds_read_b128 v[186:189], v195 offset:18432
	ds_read_b128 v[196:199], v195 offset:19456
	ds_read_b128 v[204:207], v195 offset:20480
	ds_read_b128 v[208:211], v195 offset:21504
	ds_read_b128 v[212:215], v195 offset:22528
	ds_read_b128 v[226:229], v195 offset:23552
	global_load_lds_dwordx4 v[190:191], off
	s_add_i32 m0, s43, 0x2000
	s_add_u32 s44, s8, 0x80000
	v_lshl_add_u64 v[230:231], s[8:9], 0, v[150:151]
	s_addc_u32 s45, s9, 0
	s_add_i32 s43, s48, s54
	global_load_lds_dwordx4 v[230:231], off
	v_lshl_add_u64 v[4:5], s[44:45], 0, v[154:155]
	s_mov_b32 m0, s43
	v_lshl_add_u64 v[232:233], s[10:11], 0, v[156:157]
	global_load_lds_dwordx4 v[4:5], off
	v_lshl_add_u64 v[4:5], s[44:45], 0, v[150:151]
	s_add_i32 m0, s43, 0x2000
	v_lshl_add_u64 v[234:235], s[10:11], 0, v[152:153]
	global_load_lds_dwordx4 v[4:5], off
	s_mov_b32 m0, s55
	s_nop 0
	global_load_lds_dwordx4 v[232:233], off
	s_mov_b32 m0, s56
	s_nop 0
	global_load_lds_dwordx4 v[234:235], off
	s_waitcnt vmcnt(8)
	s_waitcnt lgkmcnt(0)
	s_barrier
	v_mfma_i32_16x16x64_i8 v[82:85], v[30:33], v[178:181], 0
	v_mfma_i32_16x16x64_i8 v[78:81], v[46:49], v[178:181], 0
	v_mfma_i32_16x16x64_i8 v[66:69], v[30:33], v[186:189], 0
	v_mfma_i32_16x16x64_i8 v[62:65], v[46:49], v[186:189], 0
	v_mfma_i32_16x16x64_i8 v[42:45], v[30:33], v[204:207], 0
	v_mfma_i32_16x16x64_i8 v[38:41], v[46:49], v[204:207], 0
	v_mfma_i32_16x16x64_i8 v[18:21], v[30:33], v[212:215], 0
	v_mfma_i32_16x16x64_i8 v[14:17], v[46:49], v[212:215], 0
	v_mfma_i32_16x16x64_i8 v[82:85], v[34:37], v[182:185], v[82:85]
	v_mfma_i32_16x16x64_i8 v[78:81], v[50:53], v[182:185], v[78:81]
	v_mfma_i32_16x16x64_i8 v[66:69], v[34:37], v[196:199], v[66:69]
	v_mfma_i32_16x16x64_i8 v[62:65], v[50:53], v[196:199], v[62:65]
	v_mfma_i32_16x16x64_i8 v[42:45], v[34:37], v[208:211], v[42:45]
	v_mfma_i32_16x16x64_i8 v[38:41], v[50:53], v[208:211], v[38:41]
	v_mfma_i32_16x16x64_i8 v[18:21], v[34:37], v[226:229], v[18:21]
	v_mfma_i32_16x16x64_i8 v[14:17], v[50:53], v[226:229], v[14:17]
	v_mfma_i32_16x16x64_i8 v[26:29], v[162:165], v[204:207], 0
	v_mfma_i32_16x16x64_i8 v[22:25], v[170:173], v[204:207], 0
	v_mfma_i32_16x16x64_i8 v[10:13], v[162:165], v[212:215], 0
	v_mfma_i32_16x16x64_i8 v[4:7], v[170:173], v[212:215], 0
	v_mfma_i32_16x16x64_i8 v[30:33], v[162:165], v[178:181], 0
	v_mfma_i32_16x16x64_i8 v[34:37], v[170:173], v[178:181], 0
	v_mfma_i32_16x16x64_i8 v[46:49], v[162:165], v[186:189], 0
	v_mfma_i32_16x16x64_i8 v[50:53], v[170:173], v[186:189], 0
	v_mfma_i32_16x16x64_i8 v[26:29], v[166:169], v[208:211], v[26:29]
	v_mfma_i32_16x16x64_i8 v[22:25], v[174:177], v[208:211], v[22:25]
	v_mfma_i32_16x16x64_i8 v[10:13], v[166:169], v[226:229], v[10:13]
	v_mfma_i32_16x16x64_i8 v[4:7], v[174:177], v[226:229], v[4:7]
	v_mfma_i32_16x16x64_i8 v[30:33], v[166:169], v[182:185], v[30:33]
	v_mfma_i32_16x16x64_i8 v[34:37], v[174:177], v[182:185], v[34:37]
	v_mfma_i32_16x16x64_i8 v[46:49], v[166:169], v[196:199], v[46:49]
	v_mfma_i32_16x16x64_i8 v[50:53], v[174:177], v[196:199], v[50:53]
	s_barrier
	s_add_i32 s43, 0, 0x18000
	v_add_u32_e32 v2, s43, v194
	s_add_i32 s44, 0, 0x1c000
	ds_read_b128 v[54:57], v2
	ds_read_b128 v[58:61], v2 offset:1024
	ds_read_b128 v[70:73], v2 offset:2048
	ds_read_b128 v[74:77], v2 offset:3072
	v_add_u32_e32 v2, s44, v194
	ds_read_b128 v[162:165], v2
	ds_read_b128 v[166:169], v2 offset:1024
	ds_read_b128 v[170:173], v2 offset:2048
	ds_read_b128 v[174:177], v2 offset:3072
	s_add_u32 s10, s10, 0x80000
	s_addc_u32 s11, s11, 0
	s_mov_b32 m0, s57
	v_lshl_add_u64 v[8:9], s[10:11], 0, v[156:157]
	ds_read_b128 v[178:181], v195 offset:32768
	ds_read_b128 v[182:185], v195 offset:33792
	ds_read_b128 v[186:189], v195 offset:34816
	ds_read_b128 v[196:199], v195 offset:35840
	ds_read_b128 v[204:207], v195 offset:36864
	ds_read_b128 v[208:211], v195 offset:37888
	ds_read_b128 v[212:215], v195 offset:38912
	ds_read_b128 v[226:229], v195 offset:39936
	global_load_lds_dwordx4 v[8:9], off
	v_lshl_add_u64 v[8:9], s[10:11], 0, v[152:153]
	s_mov_b32 m0, s59
	s_nop 0
	global_load_lds_dwordx4 v[8:9], off
	s_waitcnt vmcnt(8)
	s_waitcnt lgkmcnt(0)
	s_barrier
	v_mfma_i32_16x16x64_i8 v[146:149], v[54:57], v[178:181], v[146:149]
	v_mfma_i32_16x16x64_i8 v[142:145], v[70:73], v[178:181], v[142:145]
	v_mfma_i32_16x16x64_i8 v[130:133], v[54:57], v[186:189], v[130:133]
	v_mfma_i32_16x16x64_i8 v[126:129], v[70:73], v[186:189], v[126:129]
	v_mfma_i32_16x16x64_i8 v[114:117], v[54:57], v[204:207], v[114:117]
	v_mfma_i32_16x16x64_i8 v[110:113], v[70:73], v[204:207], v[110:113]
	v_mfma_i32_16x16x64_i8 v[98:101], v[54:57], v[212:215], v[98:101]
	v_mfma_i32_16x16x64_i8 v[94:97], v[70:73], v[212:215], v[94:97]
	v_mfma_i32_16x16x64_i8 v[146:149], v[58:61], v[182:185], v[146:149]
	v_mfma_i32_16x16x64_i8 v[142:145], v[74:77], v[182:185], v[142:145]
	v_mfma_i32_16x16x64_i8 v[130:133], v[58:61], v[196:199], v[130:133]
	v_mfma_i32_16x16x64_i8 v[126:129], v[74:77], v[196:199], v[126:129]
	v_mfma_i32_16x16x64_i8 v[114:117], v[58:61], v[208:211], v[114:117]
	v_mfma_i32_16x16x64_i8 v[110:113], v[74:77], v[208:211], v[110:113]
	v_mfma_i32_16x16x64_i8 v[98:101], v[58:61], v[226:229], v[98:101]
	v_mfma_i32_16x16x64_i8 v[94:97], v[74:77], v[226:229], v[94:97]
	v_mfma_i32_16x16x64_i8 v[138:141], v[162:165], v[178:181], v[138:141]
	v_mfma_i32_16x16x64_i8 v[134:137], v[170:173], v[178:181], v[134:137]
	v_mfma_i32_16x16x64_i8 v[122:125], v[162:165], v[186:189], v[122:125]
	v_mfma_i32_16x16x64_i8 v[118:121], v[170:173], v[186:189], v[118:121]
	v_mfma_i32_16x16x64_i8 v[106:109], v[162:165], v[204:207], v[106:109]
	v_mfma_i32_16x16x64_i8 v[102:105], v[170:173], v[204:207], v[102:105]
	v_mfma_i32_16x16x64_i8 v[90:93], v[162:165], v[212:215], v[90:93]
	v_mfma_i32_16x16x64_i8 v[86:89], v[170:173], v[212:215], v[86:89]
	v_mfma_i32_16x16x64_i8 v[138:141], v[166:169], v[182:185], v[138:141]
	v_mfma_i32_16x16x64_i8 v[134:137], v[174:177], v[182:185], v[134:137]
	v_mfma_i32_16x16x64_i8 v[122:125], v[166:169], v[196:199], v[122:125]
	v_mfma_i32_16x16x64_i8 v[118:121], v[174:177], v[196:199], v[118:121]
	v_mfma_i32_16x16x64_i8 v[106:109], v[166:169], v[208:211], v[106:109]
	v_mfma_i32_16x16x64_i8 v[102:105], v[174:177], v[208:211], v[102:105]
	v_mfma_i32_16x16x64_i8 v[90:93], v[166:169], v[226:229], v[90:93]
	v_mfma_i32_16x16x64_i8 v[86:89], v[174:177], v[226:229], v[86:89]
	s_barrier
	s_add_i32 s10, s43, s54
	v_lshl_add_u64 v[8:9], v[190:191], 0, s[94:95]
	s_mov_b32 m0, s10
	ds_read_b128 v[178:181], v195 offset:49152
	ds_read_b128 v[182:185], v195 offset:50176
	ds_read_b128 v[186:189], v195 offset:51200
	ds_read_b128 v[196:199], v195 offset:52224
	ds_read_b128 v[204:207], v195 offset:53248
	ds_read_b128 v[208:211], v195 offset:54272
	ds_read_b128 v[212:215], v195 offset:55296
	ds_read_b128 v[226:229], v195 offset:56320
	global_load_lds_dwordx4 v[8:9], off
	s_add_i32 m0, s10, 0x2000
	s_add_u32 s8, s8, 0x80080
	v_lshl_add_u64 v[8:9], v[230:231], 0, s[94:95]
	s_addc_u32 s9, s9, 0
	s_add_i32 s10, s44, s54
	global_load_lds_dwordx4 v[8:9], off
	v_lshl_add_u64 v[8:9], s[8:9], 0, v[154:155]
	s_mov_b32 m0, s10
	s_nop 0
	global_load_lds_dwordx4 v[8:9], off
	v_lshl_add_u64 v[8:9], s[8:9], 0, v[150:151]
	s_add_i32 m0, s10, 0x2000
	s_nop 0
	global_load_lds_dwordx4 v[8:9], off
	v_lshl_add_u64 v[8:9], v[232:233], 0, s[94:95]
	s_mov_b32 m0, s71
	s_nop 0
	global_load_lds_dwordx4 v[8:9], off
	v_lshl_add_u64 v[8:9], v[234:235], 0, s[94:95]
	s_mov_b32 m0, s74
	s_nop 0
	global_load_lds_dwordx4 v[8:9], off
	s_waitcnt vmcnt(8)
	s_waitcnt lgkmcnt(0)
	s_barrier
	v_mfma_i32_16x16x64_i8 v[82:85], v[54:57], v[178:181], v[82:85]
	v_mfma_i32_16x16x64_i8 v[78:81], v[70:73], v[178:181], v[78:81]
	v_mfma_i32_16x16x64_i8 v[66:69], v[54:57], v[186:189], v[66:69]
	v_mfma_i32_16x16x64_i8 v[62:65], v[70:73], v[186:189], v[62:65]
	v_mfma_i32_16x16x64_i8 v[42:45], v[54:57], v[204:207], v[42:45]
	v_mfma_i32_16x16x64_i8 v[38:41], v[70:73], v[204:207], v[38:41]
	v_mfma_i32_16x16x64_i8 v[18:21], v[54:57], v[212:215], v[18:21]
	v_mfma_i32_16x16x64_i8 v[14:17], v[70:73], v[212:215], v[14:17]
	v_mfma_i32_16x16x64_i8 v[82:85], v[58:61], v[182:185], v[82:85]
	v_mfma_i32_16x16x64_i8 v[78:81], v[74:77], v[182:185], v[78:81]
	v_mfma_i32_16x16x64_i8 v[66:69], v[58:61], v[196:199], v[66:69]
	v_mfma_i32_16x16x64_i8 v[62:65], v[74:77], v[196:199], v[62:65]
	v_mfma_i32_16x16x64_i8 v[42:45], v[58:61], v[208:211], v[42:45]
	v_mfma_i32_16x16x64_i8 v[38:41], v[74:77], v[208:211], v[38:41]
	v_mfma_i32_16x16x64_i8 v[18:21], v[58:61], v[226:229], v[18:21]
	v_mfma_i32_16x16x64_i8 v[14:17], v[74:77], v[226:229], v[14:17]
	v_mfma_i32_16x16x64_i8 v[30:33], v[162:165], v[178:181], v[30:33]
	v_mfma_i32_16x16x64_i8 v[74:77], v[166:169], v[182:185], v[30:33]
	v_mfma_i32_16x16x64_i8 v[30:33], v[170:173], v[178:181], v[34:37]
	v_mfma_i32_16x16x64_i8 v[70:73], v[174:177], v[182:185], v[30:33]
	v_mfma_i32_16x16x64_i8 v[30:33], v[162:165], v[186:189], v[46:49]
	v_mfma_i32_16x16x64_i8 v[58:61], v[166:169], v[196:199], v[30:33]
	v_mfma_i32_16x16x64_i8 v[30:33], v[170:173], v[186:189], v[50:53]
	v_mfma_i32_16x16x64_i8 v[26:29], v[162:165], v[204:207], v[26:29]
	v_mfma_i32_16x16x64_i8 v[22:25], v[170:173], v[204:207], v[22:25]
	v_mfma_i32_16x16x64_i8 v[8:11], v[162:165], v[212:215], v[10:13]
	v_mfma_i32_16x16x64_i8 v[4:7], v[170:173], v[212:215], v[4:7]
	v_mfma_i32_16x16x64_i8 v[54:57], v[174:177], v[196:199], v[30:33]
	v_mfma_i32_16x16x64_i8 v[26:29], v[166:169], v[208:211], v[26:29]
	v_mfma_i32_16x16x64_i8 v[22:25], v[174:177], v[208:211], v[22:25]
	v_mfma_i32_16x16x64_i8 v[10:13], v[166:169], v[226:229], v[8:11]
	v_mfma_i32_16x16x64_i8 v[6:9], v[174:177], v[226:229], v[4:7]
	s_barrier
	s_add_i32 s42, s42, 2
	s_add_u32 s6, s6, 0x100
	s_addc_u32 s7, s7, 0
	s_add_u32 s36, s36, 0x100
	s_addc_u32 s37, s37, 0
	s_cmp_gt_u32 s42, 29

.LBB0_3459:
	s_add_i32 s27, s15, 55
	s_lshl_b32 s6, s27, 8
	s_ashr_i32 s7, s6, 31
	v_mov_b32_e32 v165, v193
	v_mov_b32_e32 v167, v192
	s_lshl_b64 s[8:9], s[6:7], 2
	s_add_u32 s8, s51, s8
	v_lshl_add_u32 v4, v165, 3, s65
	s_addc_u32 s9, s33, s9
	v_ashrrev_i32_e32 v5, 31, v4
	s_lshr_b32 m0, s55, 2
	s_sub_i32 m0, s55, m0
	s_nop 0
	v_lshlrev_b32_e32 v34, 5, v165
	v_add_u32_e32 v34, m0, v34
	v_add_u32_e32 v34, 0x20100, v34
	ds_read_b128 v[46:49], v34 offset:16
	ds_read_b128 v[50:53], v34
	ds_read_b128 v[30:33], v34 offset:144
	ds_read_b128 v[34:37], v34 offset:128
	s_cmpk_lt_i32 s15, 0xffcf
	s_cselect_b64 s[8:9], -1, 0
	s_and_b64 vcc, exec, s[8:9]
	s_cbranch_vccnz .LBB0_3481
	s_cmp_gt_u32 s27, 13
	s_mov_b64 s[44:45], -1
	s_cbranch_scc0 .LBB0_3483
	s_cmp_eq_u32 s27, 14
	s_mov_b64 s[44:45], 0
	s_cbranch_scc1 .LBB0_3482
	s_cmp_gt_u32 s27, 22
	s_mov_b64 s[36:37], -1
	s_cbranch_scc0 .LBB0_3479
	s_cmp_gt_u32 s27, 30
	s_cbranch_scc0 .LBB0_3476
	s_cmp_gt_u32 s27, 38
	s_cbranch_scc0 .LBB0_3473
	s_cmp_gt_u32 s27, 46
	s_cbranch_scc0 .LBB0_3470
	s_mov_b64 s[10:11], -1
	s_cmp_lt_u32 s15, 0xffffffc9
	s_mov_b64 s[12:13], -1
	s_cbranch_scc0 .LBB0_3468
	s_add_i32 s7, s6, 0xffffc900
	s_mov_b64 s[12:13], 0

.LBB0_3486:
	s_lshl_b32 s7, s58, 8
	s_add_i32 s7, s7, s64
	v_add_u32_e32 v162, s7, v167
	v_ashrrev_i32_e32 v163, 31, v162
	s_lshr_b32 m0, s55, 2
	s_sub_i32 m0, s55, m0
	s_nop 0
	v_lshlrev_b32_e32 v180, 2, v167
	v_add_u32_e32 v180, m0, v180
	v_add_u32_e32 v180, 0x20000, v180
	ds_read_b32 v178, v180
	ds_read_b32 v176, v180 offset:64
	ds_read_b32 v174, v180 offset:128
	ds_read_b32 v172, v180 offset:192
	ds_read_b32 v170, v180 offset:512
	ds_read_b32 v168, v180 offset:576
	ds_read_b32 v166, v180 offset:640
	ds_read_b32 v164, v180 offset:704
	v_cvt_f32_i32_e32 v147, v147
	v_cvt_f32_i32_e32 v146, v146
	v_cvt_f32_i32_e32 v143, v143
	v_cvt_f32_i32_e32 v142, v142
	s_xor_b64 s[44:45], s[10:11], -1
	s_mov_b64 s[48:49], -1
	s_mov_b32 s37, s36
	s_and_b64 vcc, exec, s[44:45]
	s_waitcnt lgkmcnt(0)
	v_pk_mul_f32 v[146:147], v[178:179], v[146:147] op_sel_hi:[0,1]
	v_pk_mul_f32 v[142:143], v[178:179], v[142:143] op_sel_hi:[0,1]
	v_pk_mul_f32 v[180:181], v[50:51], v[146:147]
	v_cvt_f32_i32_e32 v147, v149
	v_cvt_f32_i32_e32 v146, v148
	v_pk_mul_f32 v[182:183], v[46:47], v[142:143]
	v_cvt_f32_i32_e32 v143, v145
	v_cvt_f32_i32_e32 v142, v144
	v_pk_mul_f32 v[146:147], v[178:179], v[146:147] op_sel_hi:[0,1]
	v_pk_mul_f32 v[148:149], v[52:53], v[146:147]
	v_pk_mul_f32 v[142:143], v[178:179], v[142:143] op_sel_hi:[0,1]
	v_pk_mul_f32 v[184:185], v[48:49], v[142:143]
	s_cbranch_vccz .LBB0_3488
	s_mov_b32 s48, s36
	s_mov_b32 s49, s36
	v_pk_mul_f32 v[188:189], s[48:49], v[148:149]
	v_pk_mul_f32 v[144:145], s[36:37], v[180:181]
	v_pk_mul_f32 v[190:191], s[48:49], v[184:185]
	v_pk_mul_f32 v[142:143], s[36:37], v[182:183]
	s_mov_b64 s[48:49], 0

.LBB0_3843:
	s_ashr_i32 s13, s12, 31
	s_lshl_b64 s[16:17], s[12:13], 21
	s_add_u32 s16, s0, s16
	s_addc_u32 s17, s1, s17
	s_and_b64 s[18:19], s[4:5], exec
	s_cselect_b32 s13, s17, s23
	s_cselect_b32 s44, s16, s22
	s_ashr_i32 s11, s10, 31
	s_lshl_b64 s[18:19], s[10:11], 21
	s_add_u32 s18, s14, s18
	s_addc_u32 s19, s15, s19
	s_and_b64 s[24:25], s[4:5], exec
	s_cselect_b32 s11, s19, s21
	s_cselect_b32 s45, s18, s20
	s_add_u32 s46, s20, 0x100
	s_addc_u32 s47, s21, 0
	s_add_u32 s20, s22, 0xc000
	s_addc_u32 s21, s23, 0
	s_mov_b32 s48, -2
	s_add_u32 s22, s20, 0x4000
	s_addc_u32 s23, s21, 0
	s_cmp_eq_u32 s48, 60
	s_cselect_b32 s26, s44, s22
	s_cselect_b32 s27, s13, s23
	s_cselect_b32 s24, s45, s46
	s_cselect_b32 s25, s11, s47
	s_add_u32 s22, s26, 0x8000
	s_addc_u32 s23, s27, 0
	s_add_i32 s49, 0, 0x10000
	s_add_i32 s51, 0, 0x14000
	v_add_u32_e32 v158, s49, v144
	v_add_u32_e32 v174, s51, v144
	ds_read_b128 v[146:149], v158
	ds_read_b128 v[150:153], v158 offset:1024
	ds_read_b128 v[154:157], v158 offset:2048
	ds_read_b128 v[158:161], v158 offset:3072
	ds_read_b128 v[162:165], v174
	ds_read_b128 v[166:169], v174 offset:1024
	ds_read_b128 v[170:173], v174 offset:2048
	ds_read_b128 v[174:177], v174 offset:3072
	v_lshl_add_u64 v[198:199], s[20:21], 0, v[138:139]
	s_add_i32 m0, s29, 0xc000
	ds_read_b128 v[178:181], v145
	ds_read_b128 v[182:185], v145 offset:1024
	ds_read_b128 v[186:189], v145 offset:2048
	ds_read_b128 v[190:193], v145 offset:3072
	ds_read_b128 v[194:197], v145 offset:4096
	ds_read_b128 v[204:207], v145 offset:5120
	ds_read_b128 v[208:211], v145 offset:6144
	ds_read_b128 v[212:215], v145 offset:7168
	global_load_lds_dwordx4 v[198:199], off
	v_lshl_add_u64 v[198:199], s[20:21], 0, v[140:141]
	s_add_i32 m0, s29, 0xe000
	s_nop 0
	global_load_lds_dwordx4 v[198:199], off
	s_waitcnt vmcnt(8)
	s_waitcnt lgkmcnt(0)
	s_barrier
	v_mfma_f32_16x16x32_bf16 v[128:131], v[146:149], v[178:181], 0
	v_mfma_f32_16x16x32_bf16 v[124:127], v[154:157], v[178:181], 0
	v_mfma_f32_16x16x32_bf16 v[120:123], v[146:149], v[186:189], 0
	v_mfma_f32_16x16x32_bf16 v[116:119], v[154:157], v[186:189], 0
	v_mfma_f32_16x16x32_bf16 v[104:107], v[146:149], v[194:197], 0
	v_mfma_f32_16x16x32_bf16 v[100:103], v[154:157], v[194:197], 0
	v_mfma_f32_16x16x32_bf16 v[88:91], v[146:149], v[208:211], 0
	v_mfma_f32_16x16x32_bf16 v[84:87], v[154:157], v[208:211], 0
	v_mfma_f32_16x16x32_bf16 v[128:131], v[150:153], v[182:185], v[128:131]
	v_mfma_f32_16x16x32_bf16 v[124:127], v[158:161], v[182:185], v[124:127]
	v_mfma_f32_16x16x32_bf16 v[120:123], v[150:153], v[190:193], v[120:123]
	v_mfma_f32_16x16x32_bf16 v[116:119], v[158:161], v[190:193], v[116:119]
	v_mfma_f32_16x16x32_bf16 v[104:107], v[150:153], v[204:207], v[104:107]
	v_mfma_f32_16x16x32_bf16 v[100:103], v[158:161], v[204:207], v[100:103]
	v_mfma_f32_16x16x32_bf16 v[88:91], v[150:153], v[212:215], v[88:91]
	v_mfma_f32_16x16x32_bf16 v[84:87], v[158:161], v[212:215], v[84:87]
	v_mfma_f32_16x16x32_bf16 v[112:115], v[162:165], v[178:181], 0
	v_mfma_f32_16x16x32_bf16 v[108:111], v[170:173], v[178:181], 0
	v_mfma_f32_16x16x32_bf16 v[96:99], v[162:165], v[186:189], 0
	v_mfma_f32_16x16x32_bf16 v[92:95], v[170:173], v[186:189], 0
	v_mfma_f32_16x16x32_bf16 v[80:83], v[162:165], v[194:197], 0
	v_mfma_f32_16x16x32_bf16 v[76:79], v[170:173], v[194:197], 0
	v_mfma_f32_16x16x32_bf16 v[72:75], v[162:165], v[208:211], 0
	v_mfma_f32_16x16x32_bf16 v[68:71], v[170:173], v[208:211], 0
	v_mfma_f32_16x16x32_bf16 v[112:115], v[166:169], v[182:185], v[112:115]
	v_mfma_f32_16x16x32_bf16 v[108:111], v[174:177], v[182:185], v[108:111]
	v_mfma_f32_16x16x32_bf16 v[96:99], v[166:169], v[190:193], v[96:99]
	v_mfma_f32_16x16x32_bf16 v[92:95], v[174:177], v[190:193], v[92:95]
	v_mfma_f32_16x16x32_bf16 v[80:83], v[166:169], v[204:207], v[80:83]
	v_mfma_f32_16x16x32_bf16 v[76:79], v[174:177], v[204:207], v[76:79]
	v_mfma_f32_16x16x32_bf16 v[72:75], v[166:169], v[212:215], v[72:75]
	v_mfma_f32_16x16x32_bf16 v[68:71], v[174:177], v[212:215], v[68:71]
	s_barrier
	s_add_i32 s49, s49, s28
	v_lshl_add_u64 v[198:199], s[24:25], 0, v[2:3]
	s_mov_b32 m0, s49
	ds_read_b128 v[178:181], v145 offset:16384
	ds_read_b128 v[182:185], v145 offset:17408
	ds_read_b128 v[186:189], v145 offset:18432
	ds_read_b128 v[190:193], v145 offset:19456
	ds_read_b128 v[194:197], v145 offset:20480
	ds_read_b128 v[204:207], v145 offset:21504
	ds_read_b128 v[208:211], v145 offset:22528
	ds_read_b128 v[212:215], v145 offset:23552
	global_load_lds_dwordx4 v[198:199], off
	s_add_i32 m0, s49, 0x2000
	s_add_u32 s52, s24, 0x100000
	v_lshl_add_u64 v[226:227], s[24:25], 0, v[132:133]
	s_addc_u32 s53, s25, 0
	s_add_i32 s49, s51, s28
	global_load_lds_dwordx4 v[226:227], off
	v_lshl_add_u64 v[228:229], s[52:53], 0, v[2:3]
	s_mov_b32 m0, s49
	s_nop 0
	global_load_lds_dwordx4 v[228:229], off
	v_lshl_add_u64 v[228:229], s[52:53], 0, v[132:133]
	s_add_i32 m0, s49, 0x2000
	s_nop 0
	global_load_lds_dwordx4 v[228:229], off
	v_lshl_add_u64 v[228:229], s[26:27], 0, v[136:137]
	s_mov_b32 m0, s29
	s_nop 0
	global_load_lds_dwordx4 v[228:229], off
	v_lshl_add_u64 v[228:229], s[26:27], 0, v[134:135]
	s_mov_b32 m0, s30
	s_nop 0
	global_load_lds_dwordx4 v[228:229], off
	s_waitcnt vmcnt(8)
	s_waitcnt lgkmcnt(0)
	s_barrier
	v_mfma_f32_16x16x32_bf16 v[64:67], v[146:149], v[178:181], 0
	v_mfma_f32_16x16x32_bf16 v[60:63], v[154:157], v[178:181], 0
	v_mfma_f32_16x16x32_bf16 v[56:59], v[146:149], v[186:189], 0
	v_mfma_f32_16x16x32_bf16 v[52:55], v[154:157], v[186:189], 0
	v_mfma_f32_16x16x32_bf16 v[40:43], v[146:149], v[194:197], 0
	v_mfma_f32_16x16x32_bf16 v[36:39], v[154:157], v[194:197], 0
	v_mfma_f32_16x16x32_bf16 v[24:27], v[146:149], v[208:211], 0
	v_mfma_f32_16x16x32_bf16 v[20:23], v[154:157], v[208:211], 0
	v_mfma_f32_16x16x32_bf16 v[64:67], v[150:153], v[182:185], v[64:67]
	v_mfma_f32_16x16x32_bf16 v[60:63], v[158:161], v[182:185], v[60:63]
	v_mfma_f32_16x16x32_bf16 v[56:59], v[150:153], v[190:193], v[56:59]
	v_mfma_f32_16x16x32_bf16 v[52:55], v[158:161], v[190:193], v[52:55]
	v_mfma_f32_16x16x32_bf16 v[40:43], v[150:153], v[204:207], v[40:43]
	v_mfma_f32_16x16x32_bf16 v[36:39], v[158:161], v[204:207], v[36:39]
	v_mfma_f32_16x16x32_bf16 v[24:27], v[150:153], v[212:215], v[24:27]
	v_mfma_f32_16x16x32_bf16 v[20:23], v[158:161], v[212:215], v[20:23]
	v_mfma_f32_16x16x32_bf16 v[48:51], v[162:165], v[178:181], 0
	v_mfma_f32_16x16x32_bf16 v[44:47], v[170:173], v[178:181], 0
	v_mfma_f32_16x16x32_bf16 v[32:35], v[162:165], v[186:189], 0
	v_mfma_f32_16x16x32_bf16 v[28:31], v[170:173], v[186:189], 0
	v_mfma_f32_16x16x32_bf16 v[16:19], v[162:165], v[194:197], 0
	v_mfma_f32_16x16x32_bf16 v[12:15], v[170:173], v[194:197], 0
	v_mfma_f32_16x16x32_bf16 v[8:11], v[162:165], v[208:211], 0
	v_mfma_f32_16x16x32_bf16 v[4:7], v[170:173], v[208:211], 0
	v_mfma_f32_16x16x32_bf16 v[48:51], v[166:169], v[182:185], v[48:51]
	v_mfma_f32_16x16x32_bf16 v[44:47], v[174:177], v[182:185], v[44:47]
	v_mfma_f32_16x16x32_bf16 v[32:35], v[166:169], v[190:193], v[32:35]
	v_mfma_f32_16x16x32_bf16 v[28:31], v[174:177], v[190:193], v[28:31]
	v_mfma_f32_16x16x32_bf16 v[16:19], v[166:169], v[204:207], v[16:19]
	v_mfma_f32_16x16x32_bf16 v[12:15], v[174:177], v[204:207], v[12:15]
	v_mfma_f32_16x16x32_bf16 v[8:11], v[166:169], v[212:215], v[8:11]
	v_mfma_f32_16x16x32_bf16 v[4:7], v[174:177], v[212:215], v[4:7]
	s_barrier
	s_add_i32 s49, 0, 0x18000
	s_add_i32 s51, 0, 0x1c000
	v_add_u32_e32 v158, s49, v144
	v_add_u32_e32 v174, s51, v144
	ds_read_b128 v[146:149], v158
	ds_read_b128 v[150:153], v158 offset:1024
	ds_read_b128 v[154:157], v158 offset:2048
	ds_read_b128 v[158:161], v158 offset:3072
	ds_read_b128 v[162:165], v174
	ds_read_b128 v[166:169], v174 offset:1024
	ds_read_b128 v[170:173], v174 offset:2048
	ds_read_b128 v[174:177], v174 offset:3072
	s_add_u32 s26, s26, 0x4000
	s_addc_u32 s27, s27, 0
	s_mov_b32 m0, s31
	v_lshl_add_u64 v[228:229], s[26:27], 0, v[136:137]
	ds_read_b128 v[178:181], v145 offset:32768
	ds_read_b128 v[182:185], v145 offset:33792
	ds_read_b128 v[186:189], v145 offset:34816
	ds_read_b128 v[190:193], v145 offset:35840
	ds_read_b128 v[194:197], v145 offset:36864
	ds_read_b128 v[204:207], v145 offset:37888
	ds_read_b128 v[208:211], v145 offset:38912
	ds_read_b128 v[212:215], v145 offset:39936
	global_load_lds_dwordx4 v[228:229], off
	v_lshl_add_u64 v[228:229], s[26:27], 0, v[134:135]
	s_mov_b32 m0, s33
	s_nop 0
	global_load_lds_dwordx4 v[228:229], off
	s_waitcnt vmcnt(8)
	s_waitcnt lgkmcnt(0)
	s_barrier
	v_mfma_f32_16x16x32_bf16 v[128:131], v[146:149], v[178:181], v[128:131]
	v_mfma_f32_16x16x32_bf16 v[124:127], v[154:157], v[178:181], v[124:127]
	v_mfma_f32_16x16x32_bf16 v[120:123], v[146:149], v[186:189], v[120:123]
	v_mfma_f32_16x16x32_bf16 v[116:119], v[154:157], v[186:189], v[116:119]
	v_mfma_f32_16x16x32_bf16 v[104:107], v[146:149], v[194:197], v[104:107]
	v_mfma_f32_16x16x32_bf16 v[100:103], v[154:157], v[194:197], v[100:103]
	v_mfma_f32_16x16x32_bf16 v[88:91], v[146:149], v[208:211], v[88:91]
	v_mfma_f32_16x16x32_bf16 v[84:87], v[154:157], v[208:211], v[84:87]
	v_mfma_f32_16x16x32_bf16 v[128:131], v[150:153], v[182:185], v[128:131]
	v_mfma_f32_16x16x32_bf16 v[124:127], v[158:161], v[182:185], v[124:127]
	v_mfma_f32_16x16x32_bf16 v[120:123], v[150:153], v[190:193], v[120:123]
	v_mfma_f32_16x16x32_bf16 v[116:119], v[158:161], v[190:193], v[116:119]
	v_mfma_f32_16x16x32_bf16 v[104:107], v[150:153], v[204:207], v[104:107]
	v_mfma_f32_16x16x32_bf16 v[100:103], v[158:161], v[204:207], v[100:103]
	v_mfma_f32_16x16x32_bf16 v[88:91], v[150:153], v[212:215], v[88:91]
	v_mfma_f32_16x16x32_bf16 v[84:87], v[158:161], v[212:215], v[84:87]
	v_mfma_f32_16x16x32_bf16 v[112:115], v[162:165], v[178:181], v[112:115]
	v_mfma_f32_16x16x32_bf16 v[108:111], v[170:173], v[178:181], v[108:111]
	v_mfma_f32_16x16x32_bf16 v[96:99], v[162:165], v[186:189], v[96:99]
	v_mfma_f32_16x16x32_bf16 v[92:95], v[170:173], v[186:189], v[92:95]
	v_mfma_f32_16x16x32_bf16 v[80:83], v[162:165], v[194:197], v[80:83]
	v_mfma_f32_16x16x32_bf16 v[76:79], v[170:173], v[194:197], v[76:79]
	v_mfma_f32_16x16x32_bf16 v[72:75], v[162:165], v[208:211], v[72:75]
	v_mfma_f32_16x16x32_bf16 v[68:71], v[170:173], v[208:211], v[68:71]
	v_mfma_f32_16x16x32_bf16 v[112:115], v[166:169], v[182:185], v[112:115]
	v_mfma_f32_16x16x32_bf16 v[108:111], v[174:177], v[182:185], v[108:111]
	v_mfma_f32_16x16x32_bf16 v[96:99], v[166:169], v[190:193], v[96:99]
	v_mfma_f32_16x16x32_bf16 v[92:95], v[174:177], v[190:193], v[92:95]
	v_mfma_f32_16x16x32_bf16 v[80:83], v[166:169], v[204:207], v[80:83]
	v_mfma_f32_16x16x32_bf16 v[76:79], v[174:177], v[204:207], v[76:79]
	v_mfma_f32_16x16x32_bf16 v[72:75], v[166:169], v[212:215], v[72:75]
	v_mfma_f32_16x16x32_bf16 v[68:71], v[174:177], v[212:215], v[68:71]
	s_barrier
	s_add_i32 s26, s49, s28
	v_lshl_add_u64 v[198:199], v[198:199], 0, s[94:95]
	s_mov_b32 m0, s26
	ds_read_b128 v[178:181], v145 offset:49152
	ds_read_b128 v[182:185], v145 offset:50176
	ds_read_b128 v[186:189], v145 offset:51200
	ds_read_b128 v[190:193], v145 offset:52224
	ds_read_b128 v[194:197], v145 offset:53248
	ds_read_b128 v[204:207], v145 offset:54272
	ds_read_b128 v[208:211], v145 offset:55296
	ds_read_b128 v[212:215], v145 offset:56320
	global_load_lds_dwordx4 v[198:199], off
	s_add_i32 m0, s26, 0x2000
	s_add_u32 s24, s24, 0x100080
	v_lshl_add_u64 v[198:199], v[226:227], 0, s[94:95]
	s_addc_u32 s25, s25, 0
	s_add_i32 s26, s51, s28
	global_load_lds_dwordx4 v[198:199], off
	v_lshl_add_u64 v[198:199], s[24:25], 0, v[2:3]
	s_mov_b32 m0, s26
	s_nop 0
	global_load_lds_dwordx4 v[198:199], off
	v_lshl_add_u64 v[198:199], s[24:25], 0, v[132:133]
	s_add_i32 m0, s26, 0x2000
	s_nop 0
	global_load_lds_dwordx4 v[198:199], off
	v_lshl_add_u64 v[198:199], s[22:23], 0, v[136:137]
	s_mov_b32 m0, s37
	s_nop 0
	global_load_lds_dwordx4 v[198:199], off
	v_lshl_add_u64 v[198:199], s[22:23], 0, v[134:135]
	s_mov_b32 m0, s39
	s_nop 0
	global_load_lds_dwordx4 v[198:199], off
	s_waitcnt vmcnt(8)
	s_waitcnt lgkmcnt(0)
	s_barrier
	v_mfma_f32_16x16x32_bf16 v[64:67], v[146:149], v[178:181], v[64:67]
	v_mfma_f32_16x16x32_bf16 v[60:63], v[154:157], v[178:181], v[60:63]
	v_mfma_f32_16x16x32_bf16 v[56:59], v[146:149], v[186:189], v[56:59]
	v_mfma_f32_16x16x32_bf16 v[52:55], v[154:157], v[186:189], v[52:55]
	v_mfma_f32_16x16x32_bf16 v[40:43], v[146:149], v[194:197], v[40:43]
	v_mfma_f32_16x16x32_bf16 v[36:39], v[154:157], v[194:197], v[36:39]
	v_mfma_f32_16x16x32_bf16 v[24:27], v[146:149], v[208:211], v[24:27]
	v_mfma_f32_16x16x32_bf16 v[20:23], v[154:157], v[208:211], v[20:23]
	v_mfma_f32_16x16x32_bf16 v[64:67], v[150:153], v[182:185], v[64:67]
	v_mfma_f32_16x16x32_bf16 v[60:63], v[158:161], v[182:185], v[60:63]
	v_mfma_f32_16x16x32_bf16 v[56:59], v[150:153], v[190:193], v[56:59]
	v_mfma_f32_16x16x32_bf16 v[52:55], v[158:161], v[190:193], v[52:55]
	v_mfma_f32_16x16x32_bf16 v[40:43], v[150:153], v[204:207], v[40:43]
	v_mfma_f32_16x16x32_bf16 v[36:39], v[158:161], v[204:207], v[36:39]
	v_mfma_f32_16x16x32_bf16 v[24:27], v[150:153], v[212:215], v[24:27]
	v_mfma_f32_16x16x32_bf16 v[20:23], v[158:161], v[212:215], v[20:23]
	v_mfma_f32_16x16x32_bf16 v[48:51], v[162:165], v[178:181], v[48:51]
	v_mfma_f32_16x16x32_bf16 v[44:47], v[170:173], v[178:181], v[44:47]
	v_mfma_f32_16x16x32_bf16 v[32:35], v[162:165], v[186:189], v[32:35]
	v_mfma_f32_16x16x32_bf16 v[28:31], v[170:173], v[186:189], v[28:31]
	v_mfma_f32_16x16x32_bf16 v[16:19], v[162:165], v[194:197], v[16:19]
	v_mfma_f32_16x16x32_bf16 v[12:15], v[170:173], v[194:197], v[12:15]
	v_mfma_f32_16x16x32_bf16 v[8:11], v[162:165], v[208:211], v[8:11]
	v_mfma_f32_16x16x32_bf16 v[4:7], v[170:173], v[208:211], v[4:7]
	v_mfma_f32_16x16x32_bf16 v[48:51], v[166:169], v[182:185], v[48:51]
	v_mfma_f32_16x16x32_bf16 v[44:47], v[174:177], v[182:185], v[44:47]
	v_mfma_f32_16x16x32_bf16 v[32:35], v[166:169], v[190:193], v[32:35]
	v_mfma_f32_16x16x32_bf16 v[28:31], v[174:177], v[190:193], v[28:31]
	v_mfma_f32_16x16x32_bf16 v[16:19], v[166:169], v[204:207], v[16:19]
	v_mfma_f32_16x16x32_bf16 v[12:15], v[174:177], v[204:207], v[12:15]
	v_mfma_f32_16x16x32_bf16 v[8:11], v[166:169], v[212:215], v[8:11]
	v_mfma_f32_16x16x32_bf16 v[4:7], v[174:177], v[212:215], v[4:7]
	s_barrier
	s_add_i32 s48, s48, 2
	s_add_u32 s46, s46, 0x100
	s_addc_u32 s47, s47, 0
	s_add_u32 s20, s20, 0x10000
	s_addc_u32 s21, s21, 0
	s_cmp_gt_u32 s48, 61
